# FFN-up finish loops: running store pointer replaces per-row 64-bit mad address math; conv packed ops interleaved (2 fewer hazard nops per row)
# speedup vs baseline: 1.0241x; 1.0014x over previous
; template <bool SWAP, class Epi, bool THIN = false> ...
;     ...
;     for (int st = 0; st < ns; ++st) {
;       asm volatile("s_waitcnt vmcnt(0)" ::: "memory");
;       __builtin_amdgcn_s_barrier();
;       asm volatile("" ::: "memory");
;       if (st + 1 < ns) {
;         char* nb = smem + ((st + 1) & 1) * 65536;
;         const int ko = (st + 1) * 64;
; #pragma unroll
;         for (int i = 0; i < 4; ++i) { GLDS16(A + (size_t)(ap[i] + ko), nb + tid * 16 + i * 8192); GLDS16(Bt + (size_t)(bp[i] + ko), nb + 32768 + tid * 16 + i * 8192); }
;       }
;       const char* sa = smem + (st & 1) * 65536 + (wr * 64 + fr) * 128;
;       const char* sb = smem + (st & 1) * 65536 + 32768 + (wc * 128 + fr) * 128;
;       if constexpr (THIN) {
;         if (wc == 0) {
; #pragma unroll
;           for (int ks = 0; ks < 2; ++ks) {
;             bf16x8 af[4], bf[2];
; #pragma unroll
;             for (int m = 0; m < 4; ++m) af[m] = *(const bf16x8*)(sa + m * 2048 + (((ks * 4 + fq) ^ swz) << 4));
; #pragma unroll
;             for (int n = 0; n < 2; ++n) bf[n] = *(const bf16x8*)(sb + n * 2048 + (((ks * 4 + fq) ^ swz) << 4));
; #pragma unroll
;             for (int m = 0; m < 4; ++m)
; #pragma unroll
;               for (int n = 0; n < 2; ++n)
;                 acc[m][n] = SWAP ? __builtin_amdgcn_mfma_f32_16x16x32_bf16(bf[n], af[m], acc[m][n], 0, 0, 0)
;                                  : __builtin_amdgcn_mfma_f32_16x16x32_bf16(af[m], bf[n], acc[m][n], 0, 0, 0);
;           }
;         }
;       } else {
;       bf16x8 afA[4], afB[4], bfb[2][2];
; #pragma unroll
;       for (int m = 0; m < 4; ++m) afA[m] = *(const bf16x8*)(sa + m * 2048 + ((fq ^ swz) << 4));
; #pragma unroll
;       for (int n = 0; n < 2; ++n) bfb[0][n] = *(const bf16x8*)(sb + n * 2048 + ((fq ^ swz) << 4));
; #pragma unroll
;       for (int gq = 0; gq < 8; ++gq) {
;         const int ks = gq >> 2, nh = gq & 3;
;         if (gq < 7) {
;           const int ks2 = (gq + 1) >> 2, nh2 = (gq + 1) & 3;
; #pragma unroll
;           for (int n = 0; n < 2; ++n) bfb[(gq + 1) & 1][n] = *(const bf16x8*)(sb + (nh2 * 2 + n) * 2048 + (((ks2 * 4 + fq) ^ swz) << 4));
;         }
;         if (gq == 3) {
; #pragma unroll
;           for (int m = 0; m < 4; ++m) afB[m] = *(const bf16x8*)(sa + m * 2048 + (((4 + fq) ^ swz) << 4));
;         }
;         __builtin_amdgcn_sched_barrier(0);
; #pragma unroll
.LBB0_2334:
	s_add_i32 s8, s7, 0x10000
	s_and_b32 s9, s8, 0x10000
	v_add_u32_e32 v170, s9, v135
	s_nop 0
	v_readfirstlane_b32 s9, v170
	s_waitcnt vmcnt(0)
	s_barrier
	s_and_b32 s7, s7, 0x10000
	v_or_b32_e32 v204, s7, v139
	v_add_u32_e32 v205, v204, v140
	v_add_u32_e32 v136, s7, v138
	v_add_u32_e32 v180, v136, v140
	ds_read_b128 v[168:171], v180
	ds_read_b128 v[172:175], v180 offset:2048
	ds_read_b128 v[176:179], v180 offset:4096
	ds_read_b128 v[180:183], v180 offset:6144
	ds_read_b128 v[184:187], v205 offset:32768
	ds_read_b128 v[188:191], v205 offset:34816
	ds_read_b128 v[192:195], v205 offset:36864
	ds_read_b128 v[196:199], v205 offset:38912
	v_add_u32_e32 v136, v136, v141
	s_waitcnt lgkmcnt(3)
	v_mfma_f32_16x16x32_bf16 v[126:129], v[184:187], v[168:171], v[126:129]
	s_mov_b32 m0, s9
	v_mfma_f32_16x16x32_bf16 v[110:113], v[184:187], v[172:175], v[110:113]
	global_load_lds_dwordx4 v167, s[16:17]
	v_add_u32_e32 v167, 0x80, v167
	v_mfma_f32_16x16x32_bf16 v[82:85], v[184:187], v[176:179], v[82:85]
	v_mfma_f32_16x16x32_bf16 v[50:53], v[184:187], v[180:183], v[50:53]
	ds_read_b128 v[184:187], v205 offset:40960
	ds_read_b128 v[200:203], v205 offset:43008
	s_waitcnt lgkmcnt(4)
	v_mfma_f32_16x16x32_bf16 v[122:125], v[188:191], v[168:171], v[122:125]
	s_add_u32 m0, s9, 0x8000
	v_mfma_f32_16x16x32_bf16 v[106:109], v[188:191], v[172:175], v[106:109]
	global_load_lds_dwordx4 v166, s[18:19]
	v_add_u32_e32 v166, 0x80, v166
	v_mfma_f32_16x16x32_bf16 v[78:81], v[188:191], v[176:179], v[78:81]
	v_mfma_f32_16x16x32_bf16 v[42:45], v[188:191], v[180:183], v[42:45]
	s_waitcnt lgkmcnt(3)
	v_mfma_f32_16x16x32_bf16 v[118:121], v[192:195], v[168:171], v[118:121]
	s_add_u32 m0, s9, 0x2000
	v_mfma_f32_16x16x32_bf16 v[94:97], v[192:195], v[172:175], v[94:97]
	global_load_lds_dwordx4 v165, s[16:17]
	v_add_u32_e32 v165, 0x80, v165
	v_mfma_f32_16x16x32_bf16 v[58:61], v[192:195], v[176:179], v[58:61]
	v_mfma_f32_16x16x32_bf16 v[26:29], v[192:195], v[180:183], v[26:29]
	ds_read_b128 v[188:191], v205 offset:45056
	ds_read_b128 v[192:195], v205 offset:47104
	s_waitcnt lgkmcnt(4)
	v_mfma_f32_16x16x32_bf16 v[114:117], v[196:199], v[168:171], v[114:117]
	s_add_u32 m0, s9, 0xa000
	v_mfma_f32_16x16x32_bf16 v[90:93], v[196:199], v[172:175], v[90:93]
	global_load_lds_dwordx4 v164, s[18:19]
	v_add_u32_e32 v164, 0x80, v164
	v_mfma_f32_16x16x32_bf16 v[54:57], v[196:199], v[176:179], v[54:57]
	v_mfma_f32_16x16x32_bf16 v[22:25], v[196:199], v[180:183], v[22:25]
	v_add_u32_e32 v220, v204, v141
	s_waitcnt lgkmcnt(3)
	v_mfma_f32_16x16x32_bf16 v[102:105], v[184:187], v[168:171], v[102:105]
	ds_read_b128 v[196:199], v220 offset:32768
	ds_read_b128 v[204:207], v220 offset:34816
	s_add_u32 m0, s9, 0x4000
	v_mfma_f32_16x16x32_bf16 v[74:77], v[184:187], v[172:175], v[74:77]
	global_load_lds_dwordx4 v163, s[16:17]
	v_add_u32_e32 v163, 0x80, v163
	v_mfma_f32_16x16x32_bf16 v[46:49], v[184:187], v[176:179], v[46:49]
	v_mfma_f32_16x16x32_bf16 v[10:13], v[184:187], v[180:183], v[10:13]
	ds_read_b128 v[184:187], v136
	ds_read_b128 v[208:211], v136 offset:2048
	ds_read_b128 v[212:215], v136 offset:4096
	ds_read_b128 v[216:219], v136 offset:6144
	s_waitcnt lgkmcnt(8)
	v_mfma_f32_16x16x32_bf16 v[98:101], v[200:203], v[168:171], v[98:101]
	s_add_u32 m0, s9, 0xc000
	v_mfma_f32_16x16x32_bf16 v[66:69], v[200:203], v[172:175], v[66:69]
	global_load_lds_dwordx4 v162, s[18:19]
	v_add_u32_e32 v162, 0x80, v162
	v_mfma_f32_16x16x32_bf16 v[30:33], v[200:203], v[176:179], v[30:33]
	v_mfma_f32_16x16x32_bf16 v[6:9], v[200:203], v[180:183], v[6:9]
	s_waitcnt lgkmcnt(7)
	v_mfma_f32_16x16x32_bf16 v[70:73], v[188:191], v[168:171], v[70:73]
	s_add_u32 m0, s9, 0x6000
	s_waitcnt lgkmcnt(6)
	v_mfma_f32_16x16x32_bf16 v[62:65], v[192:195], v[168:171], v[62:65]
	global_load_lds_dwordx4 v161, s[16:17]
	v_add_u32_e32 v161, 0x80, v161
	v_mfma_f32_16x16x32_bf16 v[38:41], v[188:191], v[172:175], v[38:41]
	v_mfma_f32_16x16x32_bf16 v[34:37], v[192:195], v[172:175], v[34:37]
	ds_read_b128 v[168:171], v220 offset:36864
	ds_read_b128 v[172:175], v220 offset:38912
	v_mfma_f32_16x16x32_bf16 v[18:21], v[188:191], v[176:179], v[18:21]
	s_add_u32 m0, s9, 0xe000
	v_mfma_f32_16x16x32_bf16 v[14:17], v[192:195], v[176:179], v[14:17]
	global_load_lds_dwordx4 v160, s[18:19]
	v_add_u32_e32 v160, 0x80, v160
	v_mfma_f32_16x16x32_bf16 v[2:5], v[188:191], v[180:183], v[2:5]
	v_mfma_f32_16x16x32_bf16 v[86:89], v[192:195], v[180:183], v[86:89]
	ds_read_b128 v[176:179], v220 offset:40960
	ds_read_b128 v[180:183], v220 offset:43008
	s_waitcnt lgkmcnt(7)
	v_mfma_f32_16x16x32_bf16 v[126:129], v[196:199], v[184:187], v[126:129]
	v_mfma_f32_16x16x32_bf16 v[122:125], v[204:207], v[184:187], v[122:125]
	s_waitcnt lgkmcnt(6)
	v_mfma_f32_16x16x32_bf16 v[110:113], v[196:199], v[208:211], v[110:113]
	v_mfma_f32_16x16x32_bf16 v[106:109], v[204:207], v[208:211], v[106:109]
	s_waitcnt lgkmcnt(5)
	v_mfma_f32_16x16x32_bf16 v[82:85], v[196:199], v[212:215], v[82:85]
	v_mfma_f32_16x16x32_bf16 v[78:81], v[204:207], v[212:215], v[78:81]
	s_waitcnt lgkmcnt(4)
	v_mfma_f32_16x16x32_bf16 v[50:53], v[196:199], v[216:219], v[50:53]
	v_mfma_f32_16x16x32_bf16 v[42:45], v[204:207], v[216:219], v[42:45]
	s_waitcnt lgkmcnt(3)
	v_mfma_f32_16x16x32_bf16 v[118:121], v[168:171], v[184:187], v[118:121]
	v_mfma_f32_16x16x32_bf16 v[94:97], v[168:171], v[208:211], v[94:97]
	v_mfma_f32_16x16x32_bf16 v[58:61], v[168:171], v[212:215], v[58:61]
	v_mfma_f32_16x16x32_bf16 v[26:29], v[168:171], v[216:219], v[26:29]
	ds_read_b128 v[168:171], v220 offset:45056
	ds_read_b128 v[188:191], v220 offset:47104
	s_waitcnt lgkmcnt(4)
; template <bool SWAP, class Epi, bool THIN = false> ...
;     ...
;     for (int st = 0; st < ns; ++st) {
;       asm volatile("s_waitcnt vmcnt(0)" ::: "memory");
;       __builtin_amdgcn_s_barrier();
;       asm volatile("" ::: "memory");
;       if (st + 1 < ns) {
;         char* nb = smem + ((st + 1) & 1) * 65536;
;         const int ko = (st + 1) * 64;
; #pragma unroll
;         for (int i = 0; i < 4; ++i) { GLDS16(A + (size_t)(ap[i] + ko), nb + tid * 16 + i * 8192); GLDS16(Bt + (size_t)(bp[i] + ko), nb + 32768 + tid * 16 + i * 8192); }
;       }
;       const char* sa = smem + (st & 1) * 65536 + (wr * 64 + fr) * 128;
;       const char* sb = smem + (st & 1) * 65536 + 32768 + (wc * 128 + fr) * 128;
;       if constexpr (THIN) {
;         if (wc == 0) {
; #pragma unroll
;           for (int ks = 0; ks < 2; ++ks) {
;             bf16x8 af[4], bf[2];
; #pragma unroll
;             for (int m = 0; m < 4; ++m) af[m] = *(const bf16x8*)(sa + m * 2048 + (((ks * 4 + fq) ^ swz) << 4));
; #pragma unroll
;             for (int n = 0; n < 2; ++n) bf[n] = *(const bf16x8*)(sb + n * 2048 + (((ks * 4 + fq) ^ swz) << 4));
; #pragma unroll
;             for (int m = 0; m < 4; ++m)
; #pragma unroll
;               for (int n = 0; n < 2; ++n)
;                 acc[m][n] = SWAP ? __builtin_amdgcn_mfma_f32_16x16x32_bf16(bf[n], af[m], acc[m][n], 0, 0, 0)
;                                  : __builtin_amdgcn_mfma_f32_16x16x32_bf16(af[m], bf[n], acc[m][n], 0, 0, 0);
;           }
;         }
;       } else {
;       bf16x8 afA[4], afB[4], bfb[2][2];
; #pragma unroll
;       for (int m = 0; m < 4; ++m) afA[m] = *(const bf16x8*)(sa + m * 2048 + ((fq ^ swz) << 4));
; #pragma unroll
;       for (int n = 0; n < 2; ++n) bfb[0][n] = *(const bf16x8*)(sb + n * 2048 + ((fq ^ swz) << 4));
; #pragma unroll
;       for (int gq = 0; gq < 8; ++gq) {
;         const int ks = gq >> 2, nh = gq & 3;
;         if (gq < 7) {
;           const int ks2 = (gq + 1) >> 2, nh2 = (gq + 1) & 3;
; #pragma unroll
;           for (int n = 0; n < 2; ++n) bfb[(gq + 1) & 1][n] = *(const bf16x8*)(sb + (nh2 * 2 + n) * 2048 + (((ks2 * 4 + fq) ^ swz) << 4));
;         }
;         if (gq == 3) {
; #pragma unroll
;           for (int m = 0; m < 4; ++m) afB[m] = *(const bf16x8*)(sa + m * 2048 + (((4 + fq) ^ swz) << 4));
;         }
;         __builtin_amdgcn_sched_barrier(0);
; #pragma unroll
	v_mfma_f32_16x16x32_bf16 v[114:117], v[172:175], v[184:187], v[114:117]
	v_mfma_f32_16x16x32_bf16 v[90:93], v[172:175], v[208:211], v[90:93]
	v_mfma_f32_16x16x32_bf16 v[54:57], v[172:175], v[212:215], v[54:57]
	v_mfma_f32_16x16x32_bf16 v[22:25], v[172:175], v[216:219], v[22:25]
	s_waitcnt lgkmcnt(3)
	v_mfma_f32_16x16x32_bf16 v[102:105], v[176:179], v[184:187], v[102:105]
	s_waitcnt lgkmcnt(2)
	v_mfma_f32_16x16x32_bf16 v[98:101], v[180:183], v[184:187], v[98:101]
	v_mfma_f32_16x16x32_bf16 v[74:77], v[176:179], v[208:211], v[74:77]
	v_mfma_f32_16x16x32_bf16 v[66:69], v[180:183], v[208:211], v[66:69]
	v_mfma_f32_16x16x32_bf16 v[46:49], v[176:179], v[212:215], v[46:49]
	v_mfma_f32_16x16x32_bf16 v[30:33], v[180:183], v[212:215], v[30:33]
	v_mfma_f32_16x16x32_bf16 v[10:13], v[176:179], v[216:219], v[10:13]
	v_mfma_f32_16x16x32_bf16 v[6:9], v[180:183], v[216:219], v[6:9]
	s_waitcnt lgkmcnt(1)
	v_mfma_f32_16x16x32_bf16 v[70:73], v[168:171], v[184:187], v[70:73]
	s_add_i32 s5, s5, 64
	s_cmpk_eq_i32 s5, 0x3c0
	s_mov_b32 s7, s8
	s_waitcnt lgkmcnt(0)
	v_mfma_f32_16x16x32_bf16 v[62:65], v[188:191], v[184:187], v[62:65]
	v_mfma_f32_16x16x32_bf16 v[38:41], v[168:171], v[208:211], v[38:41]
	v_mfma_f32_16x16x32_bf16 v[34:37], v[188:191], v[208:211], v[34:37]
	v_mfma_f32_16x16x32_bf16 v[18:21], v[168:171], v[212:215], v[18:21]
	v_mfma_f32_16x16x32_bf16 v[14:17], v[188:191], v[212:215], v[14:17]
	v_mfma_f32_16x16x32_bf16 v[2:5], v[168:171], v[216:219], v[2:5]
	v_mfma_f32_16x16x32_bf16 v[86:89], v[188:191], v[216:219], v[86:89]
	s_cbranch_scc0 .LBB0_2334
	s_waitcnt vmcnt(0)
	s_barrier
	v_add_u32_e32 v136, v150, v140
	ds_read_b128 v[160:163], v136
	ds_read_b128 v[164:167], v136 offset:2048
	ds_read_b128 v[168:171], v136 offset:4096
	ds_read_b128 v[172:175], v136 offset:6144
	v_add_u32_e32 v136, v151, v140
	ds_read_b128 v[176:179], v136
	ds_read_b128 v[180:183], v136 offset:2048
	ds_read_b128 v[184:187], v136 offset:4096
	ds_read_b128 v[188:191], v136 offset:6144
	s_waitcnt lgkmcnt(0)
	v_mfma_f32_16x16x32_bf16 v[126:129], v[176:179], v[160:163], v[126:129]
	v_mfma_f32_16x16x32_bf16 v[110:113], v[176:179], v[164:167], v[110:113]
	v_mfma_f32_16x16x32_bf16 v[82:85], v[176:179], v[168:171], v[82:85]
	v_mfma_f32_16x16x32_bf16 v[50:53], v[176:179], v[172:175], v[50:53]
	ds_read_b128 v[176:179], v136 offset:8192
	ds_read_b128 v[192:195], v136 offset:10240
	v_mfma_f32_16x16x32_bf16 v[122:125], v[180:183], v[160:163], v[122:125]
	v_mfma_f32_16x16x32_bf16 v[106:109], v[180:183], v[164:167], v[106:109]
	v_mfma_f32_16x16x32_bf16 v[78:81], v[180:183], v[168:171], v[78:81]
	v_mfma_f32_16x16x32_bf16 v[42:45], v[180:183], v[172:175], v[42:45]
	v_mfma_f32_16x16x32_bf16 v[118:121], v[184:187], v[160:163], v[118:121]
	v_mfma_f32_16x16x32_bf16 v[94:97], v[184:187], v[164:167], v[94:97]
	v_mfma_f32_16x16x32_bf16 v[58:61], v[184:187], v[168:171], v[58:61]
	v_mfma_f32_16x16x32_bf16 v[26:29], v[184:187], v[172:175], v[26:29]
	ds_read_b128 v[180:183], v136 offset:12288
	ds_read_b128 v[184:187], v136 offset:14336
	v_mfma_f32_16x16x32_bf16 v[114:117], v[188:191], v[160:163], v[114:117]
	v_mfma_f32_16x16x32_bf16 v[90:93], v[188:191], v[164:167], v[90:93]
	v_mfma_f32_16x16x32_bf16 v[54:57], v[188:191], v[168:171], v[54:57]
	v_mfma_f32_16x16x32_bf16 v[22:25], v[188:191], v[172:175], v[22:25]
	v_add_u32_e32 v136, v151, v141
	v_add_u32_e32 v208, v150, v141
	s_waitcnt lgkmcnt(0)
	v_mfma_f32_16x16x32_bf16 v[102:105], v[176:179], v[160:163], v[102:105]
	v_mfma_f32_16x16x32_bf16 v[74:77], v[176:179], v[164:167], v[74:77]
	v_mfma_f32_16x16x32_bf16 v[188:191], v[192:195], v[164:167], v[66:69]
	v_mfma_f32_16x16x32_bf16 v[196:199], v[176:179], v[168:171], v[46:49]
	s_nop 2
	ds_read_b128 v[46:49], v136
	ds_read_b128 v[66:69], v136 offset:2048
	v_mfma_f32_16x16x32_bf16 v[10:13], v[176:179], v[172:175], v[10:13]
	ds_read_b128 v[176:179], v208
	ds_read_b128 v[200:203], v208 offset:2048
	ds_read_b128 v[204:207], v208 offset:4096
	ds_read_b128 v[208:211], v208 offset:6144
	v_mfma_f32_16x16x32_bf16 v[98:101], v[192:195], v[160:163], v[98:101]
	v_mfma_f32_16x16x32_bf16 v[30:33], v[192:195], v[168:171], v[30:33]
	v_mfma_f32_16x16x32_bf16 v[6:9], v[192:195], v[172:175], v[6:9]
	v_mfma_f32_16x16x32_bf16 v[192:195], v[180:183], v[164:167], v[38:41]
	v_mfma_f32_16x16x32_bf16 v[164:167], v[184:187], v[164:167], v[34:37]
	v_mfma_f32_16x16x32_bf16 v[18:21], v[180:183], v[168:171], v[18:21]
	v_mfma_f32_16x16x32_bf16 v[168:171], v[184:187], v[168:171], v[14:17]
	s_nop 2
	ds_read_b128 v[14:17], v136 offset:4096
	ds_read_b128 v[34:37], v136 offset:6144
	v_mfma_f32_16x16x32_bf16 v[70:73], v[180:183], v[160:163], v[70:73]
	v_mfma_f32_16x16x32_bf16 v[2:5], v[180:183], v[172:175], v[2:5]
	v_mfma_f32_16x16x32_bf16 v[160:163], v[184:187], v[160:163], v[62:65]
	v_mfma_f32_16x16x32_bf16 v[86:89], v[184:187], v[172:175], v[86:89]
	s_waitcnt lgkmcnt(0)
	v_mfma_f32_16x16x32_bf16 v[172:175], v[46:49], v[208:211], v[50:53]
	s_nop 2
	ds_read_b128 v[50:53], v136 offset:8192
	ds_read_b128 v[180:183], v136 offset:10240
	v_mfma_f32_16x16x32_bf16 v[126:129], v[46:49], v[176:179], v[126:129]
	v_mfma_f32_16x16x32_bf16 v[122:125], v[66:69], v[176:179], v[122:125]
	v_mfma_f32_16x16x32_bf16 v[110:113], v[46:49], v[200:203], v[110:113]
	v_mfma_f32_16x16x32_bf16 v[106:109], v[66:69], v[200:203], v[106:109]
	v_mfma_f32_16x16x32_bf16 v[82:85], v[46:49], v[204:207], v[82:85]
	v_mfma_f32_16x16x32_bf16 v[78:81], v[66:69], v[204:207], v[78:81]
	v_mfma_f32_16x16x32_bf16 v[184:187], v[66:69], v[208:211], v[42:45]
	ds_read_b128 v[224:227], v136 offset:12288
	ds_read_b128 v[228:231], v136 offset:14336
	v_mfma_f32_16x16x32_bf16 v[118:121], v[14:17], v[176:179], v[118:121]
	v_mfma_f32_16x16x32_bf16 v[114:117], v[34:37], v[176:179], v[114:117]
	v_mfma_f32_16x16x32_bf16 v[94:97], v[14:17], v[200:203], v[94:97]
	v_mfma_f32_16x16x32_bf16 v[90:93], v[34:37], v[200:203], v[90:93]
	v_mfma_f32_16x16x32_bf16 v[212:215], v[14:17], v[204:207], v[58:61]
	v_mfma_f32_16x16x32_bf16 v[216:219], v[34:37], v[204:207], v[54:57]
	v_mfma_f32_16x16x32_bf16 v[220:223], v[14:17], v[208:211], v[26:29]
	v_mfma_f32_16x16x32_bf16 v[66:69], v[34:37], v[208:211], v[22:25]
	s_waitcnt lgkmcnt(0)
	v_mfma_f32_16x16x32_bf16 v[38:41], v[180:183], v[204:207], v[30:33]
	v_mfma_f32_16x16x32_bf16 v[62:65], v[50:53], v[176:179], v[102:105]
	v_mfma_f32_16x16x32_bf16 v[46:49], v[180:183], v[176:179], v[98:101]
	v_mfma_f32_16x16x32_bf16 v[58:61], v[50:53], v[200:203], v[74:77]
	v_mfma_f32_16x16x32_bf16 v[42:45], v[180:183], v[200:203], v[188:191]
	v_mfma_f32_16x16x32_bf16 v[54:57], v[50:53], v[204:207], v[196:199]
	v_mfma_f32_16x16x32_bf16 v[50:53], v[50:53], v[208:211], v[10:13]
	v_mfma_f32_16x16x32_bf16 v[34:37], v[180:183], v[208:211], v[6:9]
	s_nop 2
	v_mov_b32_e32 v8, v1
	s_waitcnt vmcnt(0)
	v_mfma_f32_16x16x32_bf16 v[30:33], v[224:227], v[176:179], v[70:73]
	s_barrier
; template <bool SWAP, class Epi, bool THIN = false> ...
;     ...
;     __syncthreads();
;     const int te = get_tid512();
;     const int fr_e = te & 15, fq_e = (te & 63) >> 4, wr_e = te >> 7, wc_e = (te >> 6) & 1;
;     const int sub = 2 * mt + (wr_e >> 1);
;     const int g = sub / tpg, ti = sub - g * tpg;
;     const int rig0 = ti * step - halo;
;     const int rw = (wr_e & 1) * 64;
;     if constexpr (Epi::KIND == 0) {
; #pragma unroll
;       for (int m = 0; m < 4; ++m) {
;         const int rig = rig0 + rw + m * 16 + fr_e;
;         if constexpr (Epi::ROWSUM) {
;           float ss = 0.f;
; #pragma unroll
;           for (int n = 0; n < 8; ++n) {
;             const int col = nt * 256 + wc_e * 128 + n * 16 + fq_e * 4;
;             if (col < N) ss += epi.c4(g, rig, col, acc[m][n]);
;           }
;           ss += __shfl_xor(ss, 16); ss += __shfl_xor(ss, 32);
;           if (fq_e == 0) epi.rowsum(g, rig, nt * 2 + wc_e, ss);
;         } else {
; #pragma unroll
;           for (int n = 0; n < 8; ++n) {
;             const int col = nt * 256 + wc_e * 128 + n * 16 + fq_e * 4;
;             if (col < N) epi.c4(g, rig, col, acc[m][n]);
;           }
;         }
;       }
;     } else if constexpr (Epi::KIND == 1) {
; #pragma unroll
;       for (int m = 0; m < 4; ++m) {
;         const int rig = rig0 + rw + m * 16 + fq_e * 4;
; #pragma unroll
;         for (int n = 0; n < 8; ++n) {
;           const int col = nt * 256 + wc_e * 128 + n * 16 + fr_e;
;           if (col < N) epi.r4(g, rig, col, acc[m][n]);
;         }
;       }
;     } else {
;       bf16_t* Zw = (bf16_t*)smem + ((wr_e >> 1) * 2 + wc_e) * (128 * 132);
;       const int nt2w = nt * 2 + wc_e;
; #pragma unroll
;       for (int n = 0; n < 8; ++n) {
;         const int cl = n * 16 + fq_e * 4;
;         f32x4 b4 = {0.f, 0.f, 0.f, 0.f};
;         if (epi.pre_bias) b4 = *(const f32x4*)(epi.pre_bias + epi.norig(nt2w, cl));
; #pragma unroll
;         for (int m = 0; m < 4; ++m) {
;           const int rl = rw + m * 16 + fr_e;
;           const int pos = rig0 + rl;
;           const bool ok = pos >= 0 && pos < grows;
;           f32x4 vv = acc[m][n] + b4;
;           if (!ok) vv = (f32x4){0.f, 0.f, 0.f, 0.f};
;           uint2 u; u.x = pack2(vv[0], vv[1]); u.y = pack2(vv[2], vv[3]);
;           *(uint2*)(Zw + rl * 132 + cl) = u;
;         }
	v_mfma_f32_16x16x32_bf16 v[22:25], v[224:227], v[204:207], v[18:21]
	s_nop 0
	v_ashrrev_i32_e32 v71, 8, v8
	v_add_u32_e32 v6, s4, v71
	v_mul_hi_i32 v7, v6, s26
	v_lshrrev_b32_e32 v9, 31, v7
	v_ashrrev_i32_e32 v7, 3, v7
	v_add_u32_e32 v70, v7, v9
	v_and_b32_e32 v73, 15, v8
	v_mad_u64_u32 v[6:7], s[4:5], v70, s27, v[6:7]
	v_lshrrev_b32_e32 v75, 1, v8
	v_bfe_u32 v74, v8, 6, 1
	v_mul_lo_u32 v72, v6, s28
	v_and_or_b32 v73, v75, 64, v73
	v_add_u32_e32 v98, v72, v73
	v_lshl_or_b32 v74, v71, 1, v74
	v_mul_lo_u32 v74, v74, s29
	v_add_u32_e32 v99, -1, v98
	v_mfma_f32_16x16x32_bf16 v[18:21], v[224:227], v[208:211], v[2:5]
	v_add_f32_e64 v76, v126, 0
	v_add_f32_e64 v77, v127, 0
	v_cmp_gt_u32_e32 vcc, s30, v99
	s_lshl_b32 s24, s6, 7
	v_mfma_f32_16x16x32_bf16 v[2:5], v[228:231], v[208:211], v[86:89]
	v_add_f32_e64 v84, v84, 0
	v_add_f32_e64 v85, v85, 0
	v_pk_add_f32 v[82:83], v[82:83], 0 op_sel_hi:[1,0]
	v_pk_add_f32 v[66:67], v[66:67], 0 op_sel_hi:[1,0]
	v_and_or_b32 v86, v75, 24, v74
	v_pk_add_f32 v[74:75], v[128:129], 0 op_sel_hi:[1,0]
	v_add_u32_e32 v88, 15, v98
	v_cndmask_b32_e32 v87, 0, v74, vcc
	v_cndmask_b32_e32 v75, 0, v75, vcc
	v_cndmask_b32_e32 v74, 0, v76, vcc
	v_cndmask_b32_e32 v76, 0, v77, vcc
	v_cvt_pk_bf16_f32 v74, v74, v76
	v_cvt_pk_bf16_f32 v75, v87, v75
	v_mad_u32_u24 v73, v73, s31, v86
	v_pk_add_f32 v[76:77], v[112:113], 0 op_sel_hi:[1,0]
	v_pk_add_f32 v[86:87], v[110:111], 0 op_sel_hi:[1,0]
	v_cmp_gt_u32_e64 s[4:5], s30, v88
	v_mfma_f32_16x16x32_bf16 v[26:29], v[224:227], v[200:203], v[192:195]
	v_add_f32_e64 v62, v62, 0
	v_add_f32_e64 v63, v63, 0
	v_cndmask_b32_e64 v88, 0, v76, s[4:5]
	v_cndmask_b32_e64 v76, 0, v86, s[4:5]
	v_cndmask_b32_e64 v86, 0, v87, s[4:5]
	v_cvt_pk_bf16_f32 v76, v76, v86
	v_add_u32_e32 v86, 31, v98
	v_cndmask_b32_e64 v77, 0, v77, s[4:5]
	v_cmp_gt_u32_e64 s[6:7], s30, v86
	v_cvt_pk_bf16_f32 v77, v88, v77
	v_add_u32_e32 v88, 47, v98
	v_pk_add_f32 v[86:87], v[172:173], 0 op_sel_hi:[1,0]
	v_cndmask_b32_e64 v84, 0, v84, s[6:7]
	v_cndmask_b32_e64 v85, 0, v85, s[6:7]
	v_cndmask_b32_e64 v82, 0, v82, s[6:7]
	v_cndmask_b32_e64 v83, 0, v83, s[6:7]
	v_cvt_pk_bf16_f32 v82, v82, v83
	v_cvt_pk_bf16_f32 v83, v84, v85
	v_pk_add_f32 v[84:85], v[174:175], 0 op_sel_hi:[1,0]
	v_cmp_gt_u32_e64 s[8:9], s30, v88
	v_mfma_f32_16x16x32_bf16 v[14:17], v[228:231], v[176:179], v[160:163]
	v_add_f32_e64 v28, v28, 0
	v_add_f32_e64 v29, v29, 0
	v_cndmask_b32_e64 v88, 0, v84, s[8:9]
	v_cndmask_b32_e64 v85, 0, v85, s[8:9]
	v_cndmask_b32_e64 v84, 0, v86, s[8:9]
	v_cndmask_b32_e64 v86, 0, v87, s[8:9]
	v_cvt_pk_bf16_f32 v84, v84, v86
	v_cvt_pk_bf16_f32 v85, v88, v85
	v_pk_add_f32 v[86:87], v[124:125], 0 op_sel_hi:[1,0]
	v_pk_add_f32 v[88:89], v[122:123], 0 op_sel_hi:[1,0]
	v_cndmask_b32_e32 v98, 0, v86, vcc
	v_cndmask_b32_e32 v87, 0, v87, vcc
	v_cndmask_b32_e32 v86, 0, v88, vcc
	v_cndmask_b32_e32 v88, 0, v89, vcc
	v_cvt_pk_bf16_f32 v86, v86, v88
	v_cvt_pk_bf16_f32 v87, v98, v87
	ds_write2_b64 v73, v[74:75], v[86:87] offset1:4
	v_pk_add_f32 v[74:75], v[108:109], 0 op_sel_hi:[1,0]
	v_pk_add_f32 v[86:87], v[106:107], 0 op_sel_hi:[1,0]
	v_cndmask_b32_e64 v88, 0, v74, s[4:5]
	v_cndmask_b32_e64 v75, 0, v75, s[4:5]
	v_cndmask_b32_e64 v74, 0, v86, s[4:5]
	v_cndmask_b32_e64 v86, 0, v87, s[4:5]
	v_cvt_pk_bf16_f32 v74, v74, v86
	v_cvt_pk_bf16_f32 v75, v88, v75
	v_add_u32_e32 v86, 0x1000, v73
	ds_write2_b64 v86, v[76:77], v[74:75] offset0:16 offset1:20
	v_pk_add_f32 v[74:75], v[80:81], 0 op_sel_hi:[1,0]
	v_pk_add_f32 v[76:77], v[78:79], 0 op_sel_hi:[1,0]
	v_cndmask_b32_e64 v78, 0, v74, s[6:7]
	v_cndmask_b32_e64 v75, 0, v75, s[6:7]
	v_cndmask_b32_e64 v74, 0, v76, s[6:7]
	v_cndmask_b32_e64 v76, 0, v77, s[6:7]
	v_cvt_pk_bf16_f32 v74, v74, v76
	v_cvt_pk_bf16_f32 v75, v78, v75
	v_add_u32_e32 v87, 0x2000, v73
	ds_write2_b64 v87, v[82:83], v[74:75] offset0:32 offset1:36
	v_pk_add_f32 v[74:75], v[186:187], 0 op_sel_hi:[1,0]
	v_pk_add_f32 v[76:77], v[184:185], 0 op_sel_hi:[1,0]
	v_cndmask_b32_e64 v78, 0, v74, s[8:9]
	v_cndmask_b32_e64 v75, 0, v75, s[8:9]
	v_cndmask_b32_e64 v74, 0, v76, s[8:9]
	v_cndmask_b32_e64 v76, 0, v77, s[8:9]
	v_cvt_pk_bf16_f32 v74, v74, v76
	v_cvt_pk_bf16_f32 v75, v78, v75
	v_add_u32_e32 v88, 0x3000, v73
	ds_write2_b64 v88, v[84:85], v[74:75] offset0:48 offset1:52
	v_pk_add_f32 v[74:75], v[120:121], 0 op_sel_hi:[1,0]
	v_pk_add_f32 v[76:77], v[118:119], 0 op_sel_hi:[1,0]
	v_cndmask_b32_e32 v78, 0, v74, vcc
	v_cndmask_b32_e32 v75, 0, v75, vcc
	v_cndmask_b32_e32 v74, 0, v76, vcc
	v_cndmask_b32_e32 v76, 0, v77, vcc
	v_cvt_pk_bf16_f32 v74, v74, v76
	v_cvt_pk_bf16_f32 v75, v78, v75
	v_pk_add_f32 v[76:77], v[96:97], 0 op_sel_hi:[1,0]
	v_pk_add_f32 v[78:79], v[94:95], 0 op_sel_hi:[1,0]
	v_cndmask_b32_e64 v80, 0, v76, s[4:5]
	v_cndmask_b32_e64 v77, 0, v77, s[4:5]
	v_cndmask_b32_e64 v76, 0, v78, s[4:5]
	v_cndmask_b32_e64 v78, 0, v79, s[4:5]
	v_cvt_pk_bf16_f32 v76, v76, v78
	v_cvt_pk_bf16_f32 v77, v80, v77
	v_pk_add_f32 v[78:79], v[214:215], 0 op_sel_hi:[1,0]
	v_pk_add_f32 v[80:81], v[212:213], 0 op_sel_hi:[1,0]
	v_cndmask_b32_e64 v82, 0, v78, s[6:7]
	v_cndmask_b32_e64 v79, 0, v79, s[6:7]
	v_cndmask_b32_e64 v78, 0, v80, s[6:7]
	v_cndmask_b32_e64 v80, 0, v81, s[6:7]
	v_cvt_pk_bf16_f32 v78, v78, v80
	v_cvt_pk_bf16_f32 v79, v82, v79
	v_pk_add_f32 v[80:81], v[222:223], 0 op_sel_hi:[1,0]
	v_pk_add_f32 v[82:83], v[220:221], 0 op_sel_hi:[1,0]
	v_cndmask_b32_e64 v84, 0, v80, s[8:9]
	v_cndmask_b32_e64 v81, 0, v81, s[8:9]
	v_cndmask_b32_e64 v80, 0, v82, s[8:9]
	v_cndmask_b32_e64 v82, 0, v83, s[8:9]
	v_cvt_pk_bf16_f32 v80, v80, v82
	v_cvt_pk_bf16_f32 v81, v84, v81
	v_pk_add_f32 v[82:83], v[116:117], 0 op_sel_hi:[1,0]
	v_pk_add_f32 v[84:85], v[114:115], 0 op_sel_hi:[1,0]
; __device__ __forceinline__ unsigned pack2(float a, float b) { unsigned r; asm("v_cvt_pk_bf16_f32 %0, %1, %2" : "=v"(r) : "v"(a), "v"(b)); return r; }
; template <bool SWAP, class Epi, bool THIN = false> ...
;     ...
;     } else {
;       bf16_t* Zw = (bf16_t*)smem + ((wr_e >> 1) * 2 + wc_e) * (128 * 132);
;       const int nt2w = nt * 2 + wc_e;
; #pragma unroll
;       for (int n = 0; n < 8; ++n) {
;         const int cl = n * 16 + fq_e * 4;
;         f32x4 b4 = {0.f, 0.f, 0.f, 0.f};
;         if (epi.pre_bias) b4 = *(const f32x4*)(epi.pre_bias + epi.norig(nt2w, cl));
; #pragma unroll
;         for (int m = 0; m < 4; ++m) {
;           const int rl = rw + m * 16 + fr_e;
;           const int pos = rig0 + rl;
;           const bool ok = pos >= 0 && pos < grows;
;           f32x4 vv = acc[m][n] + b4;
;           if (!ok) vv = (f32x4){0.f, 0.f, 0.f, 0.f};
;           uint2 u; u.x = pack2(vv[0], vv[1]); u.y = pack2(vv[2], vv[3]);
;           *(uint2*)(Zw + rl * 132 + cl) = u;
;         }
;       }
	v_cndmask_b32_e32 v89, 0, v82, vcc
	v_cndmask_b32_e32 v83, 0, v83, vcc
	v_cndmask_b32_e32 v82, 0, v84, vcc
	v_mfma_f32_16x16x32_bf16 v[10:13], v[228:231], v[200:203], v[164:167]
	v_cndmask_b32_e32 v84, 0, v85, vcc
	v_cvt_pk_bf16_f32 v82, v82, v84
	v_cvt_pk_bf16_f32 v83, v89, v83
	v_mfma_f32_16x16x32_bf16 v[6:9], v[228:231], v[204:207], v[168:171]
	ds_write2_b64 v73, v[74:75], v[82:83] offset0:8 offset1:12
	v_pk_add_f32 v[74:75], v[92:93], 0 op_sel_hi:[1,0]
	v_pk_add_f32 v[82:83], v[90:91], 0 op_sel_hi:[1,0]
	v_cndmask_b32_e64 v84, 0, v74, s[4:5]
	v_cndmask_b32_e64 v75, 0, v75, s[4:5]
	v_cndmask_b32_e64 v74, 0, v82, s[4:5]
	v_cndmask_b32_e64 v82, 0, v83, s[4:5]
	v_cvt_pk_bf16_f32 v74, v74, v82
	v_cvt_pk_bf16_f32 v75, v84, v75
	v_pk_add_f32 v[26:27], v[26:27], 0 op_sel_hi:[1,0]
	ds_write2_b64 v86, v[76:77], v[74:75] offset0:24 offset1:28
	v_pk_add_f32 v[74:75], v[218:219], 0 op_sel_hi:[1,0]
	v_pk_add_f32 v[76:77], v[216:217], 0 op_sel_hi:[1,0]
	v_pk_add_f32 v[58:59], v[58:59], 0 op_sel_hi:[1,0]
	v_pk_add_f32 v[54:55], v[54:55], 0 op_sel_hi:[1,0]
	v_pk_add_f32 v[50:51], v[50:51], 0 op_sel_hi:[1,0]
	v_pk_add_f32 v[46:47], v[46:47], 0 op_sel_hi:[1,0]
	v_pk_add_f32 v[42:43], v[42:43], 0 op_sel_hi:[1,0]
	v_pk_add_f32 v[38:39], v[38:39], 0 op_sel_hi:[1,0]
	v_pk_add_f32 v[34:35], v[34:35], 0 op_sel_hi:[1,0]
	v_pk_add_f32 v[30:31], v[30:31], 0 op_sel_hi:[1,0]
	v_cndmask_b32_e64 v28, 0, v28, s[4:5]
	v_cndmask_b32_e64 v26, 0, v26, s[4:5]
	v_cndmask_b32_e64 v27, 0, v27, s[4:5]
	v_pk_add_f32 v[22:23], v[22:23], 0 op_sel_hi:[1,0]
	v_pk_add_f32 v[18:19], v[18:19], 0 op_sel_hi:[1,0]
	v_pk_add_f32 v[14:15], v[14:15], 0 op_sel_hi:[1,0]
	v_pk_add_f32 v[10:11], v[10:11], 0 op_sel_hi:[1,0]
	v_pk_add_f32 v[6:7], v[6:7], 0 op_sel_hi:[1,0]
	v_pk_add_f32 v[2:3], v[2:3], 0 op_sel_hi:[1,0]
	v_cndmask_b32_e64 v82, 0, v74, s[6:7]
	v_cndmask_b32_e64 v75, 0, v75, s[6:7]
	v_cndmask_b32_e64 v74, 0, v76, s[6:7]
	v_pk_add_f32 v[68:69], v[68:69], 0 op_sel_hi:[1,0]
	v_cndmask_b32_e64 v66, 0, v66, s[8:9]
	v_cndmask_b32_e64 v67, 0, v67, s[8:9]
	v_pk_add_f32 v[64:65], v[64:65], 0 op_sel_hi:[1,0]
	v_cndmask_b32_e32 v62, 0, v62, vcc
	v_cndmask_b32_e32 v63, 0, v63, vcc
	v_pk_add_f32 v[60:61], v[60:61], 0 op_sel_hi:[1,0]
	v_cndmask_b32_e64 v58, 0, v58, s[4:5]
	v_cndmask_b32_e64 v59, 0, v59, s[4:5]
	v_pk_add_f32 v[56:57], v[56:57], 0 op_sel_hi:[1,0]
	v_cndmask_b32_e64 v54, 0, v54, s[6:7]
	v_cndmask_b32_e64 v55, 0, v55, s[6:7]
	v_pk_add_f32 v[52:53], v[52:53], 0 op_sel_hi:[1,0]
	v_cndmask_b32_e64 v50, 0, v50, s[8:9]
	v_cndmask_b32_e64 v51, 0, v51, s[8:9]
	v_pk_add_f32 v[48:49], v[48:49], 0 op_sel_hi:[1,0]
	v_cndmask_b32_e32 v46, 0, v46, vcc
	v_cndmask_b32_e32 v47, 0, v47, vcc
	v_pk_add_f32 v[44:45], v[44:45], 0 op_sel_hi:[1,0]
	v_cndmask_b32_e64 v42, 0, v42, s[4:5]
	v_cndmask_b32_e64 v43, 0, v43, s[4:5]
	v_pk_add_f32 v[40:41], v[40:41], 0 op_sel_hi:[1,0]
	v_cndmask_b32_e64 v38, 0, v38, s[6:7]
	v_cndmask_b32_e64 v39, 0, v39, s[6:7]
	v_pk_add_f32 v[36:37], v[36:37], 0 op_sel_hi:[1,0]
	v_cndmask_b32_e64 v34, 0, v34, s[8:9]
	v_cndmask_b32_e64 v35, 0, v35, s[8:9]
	v_pk_add_f32 v[32:33], v[32:33], 0 op_sel_hi:[1,0]
	v_cndmask_b32_e32 v30, 0, v30, vcc
	v_cndmask_b32_e32 v31, 0, v31, vcc
	v_cndmask_b32_e64 v29, 0, v29, s[4:5]
	v_cvt_pk_bf16_f32 v26, v26, v27
	v_cvt_pk_bf16_f32 v27, v28, v29
	v_pk_add_f32 v[24:25], v[24:25], 0 op_sel_hi:[1,0]
	v_cndmask_b32_e64 v22, 0, v22, s[6:7]
	v_cndmask_b32_e64 v23, 0, v23, s[6:7]
	v_pk_add_f32 v[20:21], v[20:21], 0 op_sel_hi:[1,0]
	v_cndmask_b32_e64 v18, 0, v18, s[8:9]
	v_cndmask_b32_e64 v19, 0, v19, s[8:9]
	v_pk_add_f32 v[16:17], v[16:17], 0 op_sel_hi:[1,0]
	v_cndmask_b32_e32 v14, 0, v14, vcc
	v_cndmask_b32_e32 v15, 0, v15, vcc
	v_pk_add_f32 v[12:13], v[12:13], 0 op_sel_hi:[1,0]
	v_cndmask_b32_e64 v10, 0, v10, s[4:5]
	v_cndmask_b32_e64 v11, 0, v11, s[4:5]
	v_pk_add_f32 v[8:9], v[8:9], 0 op_sel_hi:[1,0]
	v_cndmask_b32_e64 v6, 0, v6, s[6:7]
	v_cndmask_b32_e64 v7, 0, v7, s[6:7]
	v_pk_add_f32 v[4:5], v[4:5], 0 op_sel_hi:[1,0]
	v_cndmask_b32_e64 v2, 0, v2, s[8:9]
	v_cndmask_b32_e64 v3, 0, v3, s[8:9]
	v_mov_b32_e32 v28, v142
	v_cndmask_b32_e64 v76, 0, v77, s[6:7]
	v_cvt_pk_bf16_f32 v74, v74, v76
	v_cvt_pk_bf16_f32 v75, v82, v75
	ds_write2_b64 v87, v[78:79], v[74:75] offset0:40 offset1:44
	v_cndmask_b32_e64 v68, 0, v68, s[8:9]
	v_cndmask_b32_e64 v69, 0, v69, s[8:9]
	v_cvt_pk_bf16_f32 v66, v66, v67
	v_cvt_pk_bf16_f32 v67, v68, v69
	ds_write2_b64 v88, v[80:81], v[66:67] offset0:56 offset1:60
	v_cndmask_b32_e32 v64, 0, v64, vcc
	v_cndmask_b32_e32 v65, 0, v65, vcc
	v_cvt_pk_bf16_f32 v62, v62, v63
	v_cvt_pk_bf16_f32 v63, v64, v65
	v_cndmask_b32_e64 v60, 0, v60, s[4:5]
	v_cndmask_b32_e64 v61, 0, v61, s[4:5]
	v_cvt_pk_bf16_f32 v58, v58, v59
	v_cvt_pk_bf16_f32 v59, v60, v61
	v_cndmask_b32_e64 v56, 0, v56, s[6:7]
	v_cndmask_b32_e64 v57, 0, v57, s[6:7]
	v_cvt_pk_bf16_f32 v54, v54, v55
	v_cvt_pk_bf16_f32 v55, v56, v57
	v_cndmask_b32_e64 v52, 0, v52, s[8:9]
	v_cndmask_b32_e64 v53, 0, v53, s[8:9]
	v_cvt_pk_bf16_f32 v50, v50, v51
	v_cvt_pk_bf16_f32 v51, v52, v53
	v_cndmask_b32_e32 v48, 0, v48, vcc
	v_cndmask_b32_e32 v49, 0, v49, vcc
	v_cvt_pk_bf16_f32 v46, v46, v47
	v_cvt_pk_bf16_f32 v47, v48, v49
	ds_write2_b64 v73, v[62:63], v[46:47] offset0:16 offset1:20
	v_cndmask_b32_e64 v44, 0, v44, s[4:5]
	v_cndmask_b32_e64 v45, 0, v45, s[4:5]
	v_cvt_pk_bf16_f32 v42, v42, v43
	v_cvt_pk_bf16_f32 v43, v44, v45
	ds_write2_b64 v86, v[58:59], v[42:43] offset0:32 offset1:36
	v_cndmask_b32_e64 v40, 0, v40, s[6:7]
	v_cndmask_b32_e64 v41, 0, v41, s[6:7]
	v_cvt_pk_bf16_f32 v38, v38, v39
	v_cvt_pk_bf16_f32 v39, v40, v41
	ds_write2_b64 v87, v[54:55], v[38:39] offset0:48 offset1:52
; __device__ __forceinline__ unsigned pack2(float a, float b) { unsigned r; asm("v_cvt_pk_bf16_f32 %0, %1, %2" : "=v"(r) : "v"(a), "v"(b)); return r; }
;   template <class F>
;   __device__ __forceinline__ void finish(const bf16_t* Z, int g, int rig0, int nt, F&& pre) const {
;     ...
;     if (MODE == 0 || nt < 8) {
;       if (MODE == 0) {
;         const int f2 = (tid & 31) * 2, q8 = tid >> 5;
;         const int q0 = 1 + 16 * q8, q1 = (q0 + 16 < 127) ? q0 + 16 : 127;
;         const int na = norig(nt, f2), ng = norig(nt, 64 + f2);
;         const f32x2 a0 = *(const f32x2*)(cw + na), a1 = *(const f32x2*)(cw + NC + na), a2 = *(const f32x2*)(cw + 2 * NC + na), ab = *(const f32x2*)(cb + na);
;         const f32x2 g0 = *(const f32x2*)(cw + ng), g1 = *(const f32x2*)(cw + NC + ng), g2 = *(const f32x2*)(cw + 2 * NC + ng), gb = *(const f32x2*)(cb + ng);
;         pre();
;         f32x2 am = ldz(Z, q0 - 1, f2), ac = ldz(Z, q0, f2);
;         f32x2 gm = ldz(Z, q0 - 1, 64 + f2), gc = ldz(Z, q0, 64 + f2);
; #pragma unroll 4
;         for (int pl = q0; pl < q1; ++pl) {
;           const f32x2 an = ldz(Z, pl + 1, f2), gn = ldz(Z, pl + 1, 64 + f2);
;           const int pos = rig0 + pl;
;           if (pos < 2048) {
;             const f32x2 av = a0 * am + a1 * ac + a2 * an + ab;
;             const f32x2 gv = g0 * gm + g1 * gc + g2 * gn + gb;
;             const float s0 = av[0] * gv[0] * __builtin_amdgcn_rcpf(1.f + __expf(-gv[0]));
;             const float s1 = av[1] * gv[1] * __builtin_amdgcn_rcpf(1.f + __expf(-gv[1]));
;             *(unsigned*)(o0 + ((size_t)g * 2048 + pos) * 2816 + nt * 64 + f2) = pack2(s0, s1);
	v_cndmask_b32_e64 v36, 0, v36, s[8:9]
	v_cndmask_b32_e64 v37, 0, v37, s[8:9]
	v_cvt_pk_bf16_f32 v34, v34, v35
	v_cvt_pk_bf16_f32 v35, v36, v37
	ds_write2_b64 v88, v[50:51], v[34:35] offset0:64 offset1:68
	v_cndmask_b32_e32 v32, 0, v32, vcc
	v_cndmask_b32_e32 v33, 0, v33, vcc
	v_cvt_pk_bf16_f32 v30, v30, v31
	v_cvt_pk_bf16_f32 v31, v32, v33
	v_cndmask_b32_e64 v24, 0, v24, s[6:7]
	v_cndmask_b32_e64 v25, 0, v25, s[6:7]
	v_cvt_pk_bf16_f32 v22, v22, v23
	v_cvt_pk_bf16_f32 v23, v24, v25
	v_cndmask_b32_e64 v20, 0, v20, s[8:9]
	v_cndmask_b32_e64 v21, 0, v21, s[8:9]
	v_cvt_pk_bf16_f32 v18, v18, v19
	v_cvt_pk_bf16_f32 v19, v20, v21
	v_cndmask_b32_e32 v16, 0, v16, vcc
	v_cndmask_b32_e32 v17, 0, v17, vcc
	v_cvt_pk_bf16_f32 v14, v14, v15
	v_cvt_pk_bf16_f32 v15, v16, v17
	ds_write2_b64 v73, v[30:31], v[14:15] offset0:24 offset1:28
	v_cndmask_b32_e64 v12, 0, v12, s[4:5]
	v_cndmask_b32_e64 v13, 0, v13, s[4:5]
	v_cvt_pk_bf16_f32 v10, v10, v11
	v_cvt_pk_bf16_f32 v11, v12, v13
	ds_write2_b64 v86, v[26:27], v[10:11] offset0:40 offset1:44
	v_cndmask_b32_e64 v8, 0, v8, s[6:7]
	v_cndmask_b32_e64 v9, 0, v9, s[6:7]
	v_cvt_pk_bf16_f32 v6, v6, v7
	v_cvt_pk_bf16_f32 v7, v8, v9
	ds_write2_b64 v87, v[22:23], v[6:7] offset0:56 offset1:60
	v_cndmask_b32_e64 v4, 0, v4, s[8:9]
	v_cndmask_b32_e64 v5, 0, v5, s[8:9]
	v_cvt_pk_bf16_f32 v2, v2, v3
	v_cvt_pk_bf16_f32 v3, v4, v5
	ds_write2_b64 v88, v[18:19], v[2:3] offset0:72 offset1:76
	s_waitcnt lgkmcnt(0)
	s_barrier
	s_nop 0
	v_ashrrev_i32_e32 v29, 1, v28
	v_and_b32_e32 v38, -16, v29
	v_min_i32_e32 v2, 0x6e, v38
	v_or_b32_e32 v20, 1, v38
	v_add_u32_e32 v3, 17, v2
	v_cmp_ge_i32_e32 vcc, v20, v3
	s_and_saveexec_b64 s[4:5], vcc
	s_xor_b64 s[4:5], exec, s[4:5]
	s_ashr_i32 s25, s24, 31
	s_or_saveexec_b64 s[4:5], s[4:5]
	v_mul_i32_i24_e32 v2, 0x10800, v71
	v_mov_b64_e32 v[22:23], s[24:25]
	v_ashrrev_i32_e32 v71, 31, v70
	s_xor_b64 exec, exec, s[4:5]
	s_cbranch_execz .LBB0_2345
	v_lshlrev_b32_e32 v4, 1, v28
	v_and_b32_e32 v21, 62, v4
	v_or_b32_e32 v4, s24, v21
	s_add_i32 s6, s24, 0xb00
	v_ashrrev_i32_e32 v5, 31, v4
	v_or_b32_e32 v12, s6, v21
	v_lshlrev_b64 v[10:11], 2, v[4:5]
	v_lshl_add_u64 v[14:15], s[12:13], 0, v[10:11]
	v_lshl_add_u64 v[18:19], s[22:23], 0, v[10:11]
	v_ashrrev_i32_e32 v13, 31, v12
	v_lshl_add_u64 v[16:17], s[20:21], 0, v[10:11]
	global_load_dwordx2 v[4:5], v[14:15], off
	global_load_dwordx2 v[6:7], v[16:17], off
	global_load_dwordx2 v[8:9], v[18:19], off
	v_lshlrev_b64 v[18:19], 2, v[12:13]
	v_lshl_add_u64 v[10:11], s[14:15], 0, v[10:11]
	v_lshl_add_u64 v[22:23], s[12:13], 0, v[18:19]
	global_load_dwordx2 v[10:11], v[10:11], off
	v_lshl_add_u64 v[24:25], s[20:21], 0, v[18:19]
	v_lshl_add_u64 v[26:27], s[22:23], 0, v[18:19]
	global_load_dwordx2 v[12:13], v[22:23], off
	global_load_dwordx2 v[14:15], v[24:25], off
	global_load_dwordx2 v[16:17], v[26:27], off
	v_lshl_add_u64 v[18:19], s[14:15], 0, v[18:19]
	global_load_dwordx2 v[18:19], v[18:19], off
	s_ashr_i32 s25, s24, 31
	v_mov_b64_e32 v[106:107], s[24:25]
	v_mov_b32_e32 v117, 0
	v_lshlrev_b32_e32 v88, 1, v142
	v_and_b32_e32 v116, 62, v88
	v_add3_u32 v88, v116, s24, 64
	s_add_i32 s38, s24, 0xb40
	v_ashrrev_i32_e32 v89, 31, v88
	v_lshl_add_u64 v[90:91], v[116:117], 0, v[106:107]
	v_or_b32_e32 v96, s38, v116
	v_lshlrev_b64 v[94:95], 2, v[90:91]
	v_lshlrev_b64 v[88:89], 2, v[88:89]
	v_lshl_add_u64 v[98:99], s[12:13], 0, v[94:95]
	v_lshl_add_u64 v[102:103], s[22:23], 0, v[88:89]
	v_ashrrev_i32_e32 v97, 31, v96
	v_lshl_add_u64 v[100:101], s[20:21], 0, v[88:89]
	global_load_dwordx2 v[88:89], v[98:99], off offset:256
	global_load_dwordx2 v[90:91], v[100:101], off
	global_load_dwordx2 v[92:93], v[102:103], off
	v_lshlrev_b64 v[102:103], 2, v[96:97]
	v_lshl_add_u64 v[94:95], s[14:15], 0, v[94:95]
	v_lshl_add_u64 v[108:109], s[12:13], 0, v[102:103]
	global_load_dwordx2 v[94:95], v[94:95], off offset:256
	v_lshl_add_u64 v[110:111], s[20:21], 0, v[102:103]
	v_lshl_add_u64 v[114:115], s[22:23], 0, v[102:103]
	global_load_dwordx2 v[96:97], v[108:109], off
	global_load_dwordx2 v[98:99], v[110:111], off
	global_load_dwordx2 v[100:101], v[114:115], off
	v_lshl_add_u64 v[102:103], s[14:15], 0, v[102:103]
	global_load_dwordx2 v[102:103], v[102:103], off
	v_lshlrev_b32_e32 v136, 1, v21
	v_mul_lo_u32 v22, v38, s31
	v_mul_lo_u32 v20, v20, s31
	v_add3_u32 v22, v2, v22, v136
	v_add3_u32 v20, v2, v20, v136
	ds_read2_b32 v[22:23], v22 offset1:32
	ds_read2_b32 v[20:21], v20 offset1:32
	s_ashr_i32 s25, s24, 31
	s_lshl_b64 s[6:7], s[24:25], 1
	s_add_u32 s6, s10, s6
	s_addc_u32 s7, s11, s7
	v_lshrrev_b32_e32 v29, 4, v29
	v_and_b32_e32 v28, 31, v28
	s_waitcnt lgkmcnt(1)
	v_lshlrev_b32_e32 v32, 16, v23
	v_and_b32_e32 v33, 0xffff0000, v23
	v_lshlrev_b32_e32 v34, 16, v22
	v_and_b32_e32 v35, 0xffff0000, v22
	v_lshl_add_u64 v[22:23], s[6:7], 0, v[136:137]
	v_mad_u64_u32 v[30:31], s[6:7], v29, s33, v[2:3]
	v_lshlrev_b32_e32 v28, 2, v28
	s_waitcnt lgkmcnt(0)
	v_lshlrev_b32_e32 v24, 16, v21
	v_and_b32_e32 v25, 0xffff0000, v21
	v_lshlrev_b32_e32 v26, 16, v20
	v_and_b32_e32 v27, 0xffff0000, v20
	v_lshlrev_b64 v[20:21], 11, v[70:71]
	v_add3_u32 v39, v30, v28, s34
	s_mov_b32 s98, 0x1600
	s_mov_b32 s99, 0
	v_add_u32_e32 v48, v72, v38
	v_ashrrev_i32_e32 v49, 31, v48
	v_lshl_add_u64 v[48:49], v[20:21], 0, v[48:49]
	v_mad_u64_u32 v[50:51], s[38:39], v48, s35, v[22:23]
	v_mad_i32_i24 v51, v49, s35, v51
	s_mov_b64 s[6:7], 0
	s_waitcnt vmcnt(0)
	ds_read2_b32 v[44:45], v39 offset1:32
	s_branch .LBB0_2340
; __device__ __forceinline__ unsigned pack2(float a, float b) { unsigned r; asm("v_cvt_pk_bf16_f32 %0, %1, %2" : "=v"(r) : "v"(a), "v"(b)); return r; }
;   template <class F>
;   __device__ __forceinline__ void finish(const bf16_t* Z, int g, int rig0, int nt, F&& pre) const {
;     ...
;         for (int pl = q0; pl < q1; ++pl) {
;           const f32x2 an = ldz(Z, pl + 1, f2), gn = ldz(Z, pl + 1, 64 + f2);
;           const int pos = rig0 + pl;
;           if (pos < 2048) {
;             const f32x2 av = a0 * am + a1 * ac + a2 * an + ab;
;             const f32x2 gv = g0 * gm + g1 * gc + g2 * gn + gb;
;             const float s0 = av[0] * gv[0] * __builtin_amdgcn_rcpf(1.f + __expf(-gv[0]));
;             const float s1 = av[1] * gv[1] * __builtin_amdgcn_rcpf(1.f + __expf(-gv[1]));
;             *(unsigned*)(o0 + ((size_t)g * 2048 + pos) * 2816 + nt * 64 + f2) = pack2(s0, s1);
;           }
;           am = ac; ac = an; gm = gc; gc = gn;
;         }
.LBB0_2339:
	s_or_b64 exec, exec, s[8:9]
	v_lshl_add_u64 v[50:51], v[50:51], 0, s[98:99]
	v_add_u32_e32 v25, 3, v38
	v_add_u32_e32 v24, 2, v38
	v_cmp_ge_i32_e32 vcc, v25, v3
	v_add_u32_e32 v39, 0x210, v39
	s_or_b64 s[6:7], vcc, s[6:7]
	v_mov_b32_e32 v38, v24
	v_mov_b64_e32 v[34:35], v[30:31]
	v_mov_b64_e32 v[26:27], v[32:33]
	v_mov_b64_e32 v[32:33], v[28:29]
	v_mov_b64_e32 v[24:25], v[36:37]
	s_andn2_b64 exec, exec, s[6:7]
	s_cbranch_execz .LBB0_2344
.LBB0_2340:
	ds_read2_b32 v[46:47], v39 offset0:66 offset1:98
	v_add_u32_e32 v36, v72, v38
	v_cmp_gt_i32_e32 vcc, s30, v36
	s_waitcnt lgkmcnt(1)
	v_lshlrev_b32_e32 v30, 16, v44
	v_and_b32_e32 v31, 0xffff0000, v44
	v_lshlrev_b32_e32 v28, 16, v45
	v_and_b32_e32 v29, 0xffff0000, v45
	s_and_saveexec_b64 s[8:9], vcc
	s_cbranch_execz .LBB0_2342
	v_pk_mul_f32 v[40:41], v[6:7], v[26:27]
	v_pk_mul_f32 v[54:55], v[14:15], v[24:25]
	v_pk_fma_f32 v[34:35], v[4:5], v[34:35], v[40:41]
	v_pk_fma_f32 v[32:33], v[12:13], v[32:33], v[54:55]
	v_pk_fma_f32 v[34:35], v[8:9], v[30:31], v[34:35]
	v_pk_fma_f32 v[32:33], v[16:17], v[28:29], v[32:33]
	v_pk_add_f32 v[34:35], v[10:11], v[34:35]
	v_pk_add_f32 v[32:33], v[18:19], v[32:33]
	s_nop 0
	v_mul_f32_e32 v37, 0xbfb8aa3b, v32
	v_mul_f32_e32 v40, 0xbfb8aa3b, v33
	v_exp_f32_e32 v37, v37
	v_exp_f32_e32 v40, v40
	v_pk_mul_f32 v[32:33], v[34:35], v[32:33]
	v_add_f32_e32 v37, 1.0, v37
	v_add_f32_e32 v40, 1.0, v40
	v_rcp_f32_e32 v37, v37
	v_rcp_f32_e32 v40, v40
	v_mul_f32_e32 v32, v32, v37
	v_mul_f32_e32 v33, v33, v40
	v_cvt_pk_bf16_f32 v40, v32, v33
	s_nop 0
	global_store_dword v[50:51], v40, off
.LBB0_2342:
	s_or_b64 exec, exec, s[8:9]
	v_lshl_add_u64 v[50:51], v[50:51], 0, s[98:99]
	ds_read2_b32 v[44:45], v39 offset0:132 offset1:164
	v_add_u32_e32 v34, 1, v36
	v_cmp_gt_i32_e32 vcc, s30, v34
	s_waitcnt lgkmcnt(1)
	v_lshlrev_b32_e32 v32, 16, v46
	v_and_b32_e32 v33, 0xffff0000, v46
	v_lshlrev_b32_e32 v36, 16, v47
	v_and_b32_e32 v37, 0xffff0000, v47
	s_and_saveexec_b64 s[8:9], vcc
	s_cbranch_execz .LBB0_2339
	v_pk_mul_f32 v[40:41], v[6:7], v[30:31]
	v_pk_mul_f32 v[54:55], v[14:15], v[28:29]
	v_pk_fma_f32 v[26:27], v[4:5], v[26:27], v[40:41]
	v_pk_fma_f32 v[24:25], v[12:13], v[24:25], v[54:55]
	v_pk_fma_f32 v[26:27], v[8:9], v[32:33], v[26:27]
	v_pk_fma_f32 v[24:25], v[16:17], v[36:37], v[24:25]
	v_pk_add_f32 v[26:27], v[10:11], v[26:27]
	v_pk_add_f32 v[24:25], v[18:19], v[24:25]
	s_nop 0
	v_mul_f32_e32 v35, 0xbfb8aa3b, v24
	v_mul_f32_e32 v40, 0xbfb8aa3b, v25
	v_exp_f32_e32 v35, v35
	v_exp_f32_e32 v40, v40
	v_pk_mul_f32 v[24:25], v[26:27], v[24:25]
	v_add_f32_e32 v35, 1.0, v35
	v_add_f32_e32 v40, 1.0, v40
	v_rcp_f32_e32 v35, v35
	v_rcp_f32_e32 v40, v40
	v_mul_f32_e32 v24, v24, v35
	v_mul_f32_e32 v25, v25, v40
	v_cvt_pk_bf16_f32 v40, v24, v25
	s_nop 0
	global_store_dword v[50:51], v40, off
	s_branch .LBB0_2339

; __device__ __forceinline__ unsigned pack2(float a, float b) { unsigned r; asm("v_cvt_pk_bf16_f32 %0, %1, %2" : "=v"(r) : "v"(a), "v"(b)); return r; }
;   template <class F>
;   __device__ __forceinline__ void finish(const bf16_t* Z, int g, int rig0, int nt, F&& pre) const {
;     ...
;         f32x2 am = ldz(Z, q0 - 1, f2), ac = ldz(Z, q0, f2);
;         f32x2 gm = ldz(Z, q0 - 1, 64 + f2), gc = ldz(Z, q0, 64 + f2);
; #pragma unroll 4
;         for (int pl = q0; pl < q1; ++pl) {
;           const f32x2 an = ldz(Z, pl + 1, f2), gn = ldz(Z, pl + 1, 64 + f2);
;           const int pos = rig0 + pl;
;           if (pos < 2048) {
;             const f32x2 av = a0 * am + a1 * ac + a2 * an + ab;
;             const f32x2 gv = g0 * gm + g1 * gc + g2 * gn + gb;
;             const float s0 = av[0] * gv[0] * __builtin_amdgcn_rcpf(1.f + __expf(-gv[0]));
;             const float s1 = av[1] * gv[1] * __builtin_amdgcn_rcpf(1.f + __expf(-gv[1]));
;             *(unsigned*)(o0 + ((size_t)g * 2048 + pos) * 2816 + nt * 64 + f2) = pack2(s0, s1);
;           }
;           am = ac; ac = an; gm = gc; gc = gn;
;         }
.LBB0_2345:
	s_or_b64 exec, exec, s[4:5]
	v_mov_b32_e32 v3, v142
	s_nop 0
	v_ashrrev_i32_e32 v28, 1, v3
	v_and_b32_e32 v37, -16, v28
	v_min_i32_e32 v4, 0x6e, v37
	v_or_b32_e32 v20, 1, v37
	v_add_u32_e32 v36, 17, v4
	v_cmp_lt_i32_e32 vcc, v20, v36
	s_and_saveexec_b64 s[4:5], vcc
	s_cbranch_execz .LBB0_2328
	v_lshlrev_b32_e32 v4, 1, v3
	v_and_b32_e32 v136, 62, v4
	v_add3_u32 v4, v136, s24, 64
	s_add_i32 s6, s24, 0xb40
	v_ashrrev_i32_e32 v5, 31, v4
	v_lshl_add_u64 v[6:7], v[136:137], 0, v[22:23]
	v_or_b32_e32 v12, s6, v136
	v_lshlrev_b64 v[10:11], 2, v[6:7]
	v_lshlrev_b64 v[4:5], 2, v[4:5]
	v_lshl_add_u64 v[14:15], s[12:13], 0, v[10:11]
	v_lshl_add_u64 v[18:19], s[22:23], 0, v[4:5]
	v_ashrrev_i32_e32 v13, 31, v12
	v_lshl_add_u64 v[16:17], s[20:21], 0, v[4:5]
	v_lshlrev_b64 v[18:19], 2, v[12:13]
	v_lshl_add_u64 v[10:11], s[14:15], 0, v[10:11]
	v_lshl_add_u64 v[24:25], s[12:13], 0, v[18:19]
	v_lshl_add_u64 v[26:27], s[20:21], 0, v[18:19]
	v_lshl_add_u64 v[30:31], s[22:23], 0, v[18:19]
	v_lshl_add_u64 v[18:19], s[14:15], 0, v[18:19]
	v_mul_lo_u32 v20, v20, s31
	v_lshlrev_b32_e32 v136, 1, v136
	v_mul_lo_u32 v24, v37, s31
	v_add3_u32 v20, v2, v20, v136
	v_add3_u32 v24, v2, v24, v136
	v_add_u32_e32 v20, 0x8400, v20
	v_add_u32_e32 v24, 0x8400, v24
	ds_read2_b32 v[20:21], v20 offset1:32
	ds_read2_b32 v[34:35], v24 offset1:32
	v_lshrrev_b32_e32 v28, 4, v28
	v_mad_u64_u32 v[28:29], s[6:7], v28, s33, v[2:3]
	v_and_b32_e32 v2, 31, v3
	v_lshl_add_u64 v[22:23], v[22:23], 1, s[10:11]
	v_lshlrev_b32_e32 v2, 2, v2
	s_waitcnt lgkmcnt(1)
	v_lshlrev_b32_e32 v24, 16, v21
	v_and_b32_e32 v25, 0xffff0000, v21
	s_waitcnt lgkmcnt(0)
	v_lshlrev_b32_e32 v30, 16, v35
	v_and_b32_e32 v31, 0xffff0000, v35
	v_lshlrev_b32_e32 v26, 16, v20
	v_and_b32_e32 v27, 0xffff0000, v20
	v_lshlrev_b32_e32 v32, 16, v34
	v_and_b32_e32 v33, 0xffff0000, v34
	v_lshlrev_b64 v[20:21], 11, v[70:71]
	v_lshl_add_u64 v[22:23], v[22:23], 0, v[136:137]
	v_add3_u32 v38, v28, v2, s36
	s_mov_b32 s98, 0x1600
	s_mov_b32 s99, 0
	v_add_u32_e32 v48, v72, v37
	v_ashrrev_i32_e32 v49, 31, v48
	v_lshl_add_u64 v[48:49], v[20:21], 0, v[48:49]
	v_mad_u64_u32 v[50:51], s[24:25], v48, s35, v[22:23]
	v_mad_i32_i24 v51, v49, s35, v51
	s_mov_b64 s[6:7], 0
	ds_read2_b32 v[44:45], v38 offset1:32
	s_branch .LBB0_2348
.LBB0_2347:
	s_or_b64 exec, exec, s[8:9]
	v_lshl_add_u64 v[50:51], v[50:51], 0, s[98:99]
	v_add_u32_e32 v25, 3, v37
	v_add_u32_e32 v24, 2, v37
	v_cmp_ge_i32_e32 vcc, v25, v36
	v_add_u32_e32 v38, 0x210, v38
	s_or_b64 s[6:7], vcc, s[6:7]
	v_mov_b32_e32 v37, v24
	v_mov_b64_e32 v[32:33], v[28:29]
	v_mov_b64_e32 v[26:27], v[30:31]
	v_mov_b64_e32 v[30:31], v[2:3]
	v_mov_b64_e32 v[24:25], v[34:35]
	s_andn2_b64 exec, exec, s[6:7]
	s_cbranch_execz .LBB0_2328
.LBB0_2348:
	ds_read2_b32 v[46:47], v38 offset0:66 offset1:98
	v_add_u32_e32 v34, v72, v37
	v_cmp_gt_i32_e32 vcc, s30, v34
	s_waitcnt lgkmcnt(1)
	v_lshlrev_b32_e32 v28, 16, v44
	v_and_b32_e32 v29, 0xffff0000, v44
	v_lshlrev_b32_e32 v2, 16, v45
	v_and_b32_e32 v3, 0xffff0000, v45
	s_and_saveexec_b64 s[8:9], vcc
	s_cbranch_execz .LBB0_2350
	v_pk_mul_f32 v[40:41], v[90:91], v[26:27]
	v_pk_mul_f32 v[54:55], v[98:99], v[24:25]
	v_pk_fma_f32 v[32:33], v[88:89], v[32:33], v[40:41]
	v_pk_fma_f32 v[30:31], v[96:97], v[30:31], v[54:55]
	v_pk_fma_f32 v[32:33], v[92:93], v[28:29], v[32:33]
	v_pk_fma_f32 v[30:31], v[100:101], v[2:3], v[30:31]
	v_pk_add_f32 v[32:33], v[94:95], v[32:33]
	v_pk_add_f32 v[30:31], v[102:103], v[30:31]
	s_nop 0
	v_mul_f32_e32 v35, 0xbfb8aa3b, v30
	v_mul_f32_e32 v39, 0xbfb8aa3b, v31
	v_exp_f32_e32 v35, v35
	v_exp_f32_e32 v39, v39
	v_pk_mul_f32 v[30:31], v[32:33], v[30:31]
	v_add_f32_e32 v35, 1.0, v35
	v_add_f32_e32 v39, 1.0, v39
	v_rcp_f32_e32 v35, v35
	v_rcp_f32_e32 v39, v39
	v_mul_f32_e32 v30, v30, v35
	v_mul_f32_e32 v31, v31, v39
	v_cvt_pk_bf16_f32 v39, v30, v31
	s_nop 0
	global_store_dword v[50:51], v39, off offset:128
.LBB0_2350:
	s_or_b64 exec, exec, s[8:9]
	v_lshl_add_u64 v[50:51], v[50:51], 0, s[98:99]
	ds_read2_b32 v[44:45], v38 offset0:132 offset1:164
	v_add_u32_e32 v32, 1, v34
	v_cmp_gt_i32_e32 vcc, s30, v32
	s_waitcnt lgkmcnt(1)
	v_lshlrev_b32_e32 v30, 16, v46
	v_and_b32_e32 v31, 0xffff0000, v46
	v_lshlrev_b32_e32 v34, 16, v47
	v_and_b32_e32 v35, 0xffff0000, v47
	s_and_saveexec_b64 s[8:9], vcc
	s_cbranch_execz .LBB0_2347
	v_pk_mul_f32 v[40:41], v[90:91], v[28:29]
	v_pk_mul_f32 v[54:55], v[98:99], v[2:3]
	v_pk_fma_f32 v[26:27], v[88:89], v[26:27], v[40:41]
	v_pk_fma_f32 v[24:25], v[96:97], v[24:25], v[54:55]
	v_pk_fma_f32 v[26:27], v[92:93], v[30:31], v[26:27]
	v_pk_fma_f32 v[24:25], v[100:101], v[34:35], v[24:25]
	v_pk_add_f32 v[26:27], v[94:95], v[26:27]
	v_pk_add_f32 v[24:25], v[102:103], v[24:25]
	s_nop 0
	v_mul_f32_e32 v33, 0xbfb8aa3b, v24
	v_mul_f32_e32 v39, 0xbfb8aa3b, v25
	v_exp_f32_e32 v33, v33
	v_exp_f32_e32 v39, v39
	v_pk_mul_f32 v[24:25], v[26:27], v[24:25]
	v_add_f32_e32 v33, 1.0, v33
	v_add_f32_e32 v39, 1.0, v39
	v_rcp_f32_e32 v33, v33
	v_rcp_f32_e32 v39, v39
	v_mul_f32_e32 v24, v24, v33
	v_mul_f32_e32 v25, v25, v39
	v_cvt_pk_bf16_f32 v39, v24, v25
	s_nop 0
	global_store_dword v[50:51], v39, off offset:128
	s_branch .LBB0_2347

; template <bool SWAP, class Epi, bool THIN = false> ...
;     ...
;     for (int st = 0; st < ns; ++st) {
;       asm volatile("s_waitcnt vmcnt(0)" ::: "memory");
;       __builtin_amdgcn_s_barrier();
;       asm volatile("" ::: "memory");
;       if (st + 1 < ns) {
;         char* nb = smem + ((st + 1) & 1) * 65536;
;         const int ko = (st + 1) * 64;
; #pragma unroll
;         for (int i = 0; i < 4; ++i) { GLDS16(A + (size_t)(ap[i] + ko), nb + tid * 16 + i * 8192); GLDS16(Bt + (size_t)(bp[i] + ko), nb + 32768 + tid * 16 + i * 8192); }
;       }
;       const char* sa = smem + (st & 1) * 65536 + (wr * 64 + fr) * 128;
;       const char* sb = smem + (st & 1) * 65536 + 32768 + (wc * 128 + fr) * 128;
;       if constexpr (THIN) {
;         if (wc == 0) {
; #pragma unroll
;           for (int ks = 0; ks < 2; ++ks) {
;             bf16x8 af[4], bf[2];
; #pragma unroll
;             for (int m = 0; m < 4; ++m) af[m] = *(const bf16x8*)(sa + m * 2048 + (((ks * 4 + fq) ^ swz) << 4));
; #pragma unroll
;             for (int n = 0; n < 2; ++n) bf[n] = *(const bf16x8*)(sb + n * 2048 + (((ks * 4 + fq) ^ swz) << 4));
; #pragma unroll
;             for (int m = 0; m < 4; ++m)
; #pragma unroll
;               for (int n = 0; n < 2; ++n)
;                 acc[m][n] = SWAP ? __builtin_amdgcn_mfma_f32_16x16x32_bf16(bf[n], af[m], acc[m][n], 0, 0, 0)
;                                  : __builtin_amdgcn_mfma_f32_16x16x32_bf16(af[m], bf[n], acc[m][n], 0, 0, 0);
;           }
;         }
;       } else {
;       bf16x8 afA[4], afB[4], bfb[2][2];
; #pragma unroll
;       for (int m = 0; m < 4; ++m) afA[m] = *(const bf16x8*)(sa + m * 2048 + ((fq ^ swz) << 4));
; #pragma unroll
;       for (int n = 0; n < 2; ++n) bfb[0][n] = *(const bf16x8*)(sb + n * 2048 + ((fq ^ swz) << 4));
; #pragma unroll
;       for (int gq = 0; gq < 8; ++gq) {
;         const int ks = gq >> 2, nh = gq & 3;
;         if (gq < 7) {
;           const int ks2 = (gq + 1) >> 2, nh2 = (gq + 1) & 3;
; #pragma unroll
;           for (int n = 0; n < 2; ++n) bfb[(gq + 1) & 1][n] = *(const bf16x8*)(sb + (nh2 * 2 + n) * 2048 + (((ks2 * 4 + fq) ^ swz) << 4));
;         }
;         if (gq == 3) {
; #pragma unroll
;           for (int m = 0; m < 4; ++m) afB[m] = *(const bf16x8*)(sa + m * 2048 + (((4 + fq) ^ swz) << 4));
;         }
;         __builtin_amdgcn_sched_barrier(0);
; #pragma unroll
.LBB0_3424:
	s_add_i32 s8, s7, 0x10000
	s_and_b32 s9, s8, 0x10000
	v_add_u32_e32 v170, s9, v135
	s_nop 0
	v_readfirstlane_b32 s9, v170
	s_waitcnt vmcnt(0)
	s_barrier
	s_and_b32 s7, s7, 0x10000
	v_or_b32_e32 v204, s7, v139
	v_add_u32_e32 v205, v204, v140
	v_add_u32_e32 v136, s7, v138
	v_add_u32_e32 v180, v136, v140
	ds_read_b128 v[168:171], v180
	ds_read_b128 v[172:175], v180 offset:2048
	ds_read_b128 v[176:179], v180 offset:4096
	ds_read_b128 v[180:183], v180 offset:6144
	ds_read_b128 v[184:187], v205 offset:32768
	ds_read_b128 v[188:191], v205 offset:34816
	ds_read_b128 v[192:195], v205 offset:36864
	ds_read_b128 v[196:199], v205 offset:38912
	v_add_u32_e32 v136, v136, v141
	s_waitcnt lgkmcnt(3)
	v_mfma_f32_16x16x32_bf16 v[126:129], v[184:187], v[168:171], v[126:129]
	s_mov_b32 m0, s9
	v_mfma_f32_16x16x32_bf16 v[110:113], v[184:187], v[172:175], v[110:113]
	global_load_lds_dwordx4 v167, s[14:15]
	v_add_u32_e32 v167, 0x80, v167
	v_mfma_f32_16x16x32_bf16 v[82:85], v[184:187], v[176:179], v[82:85]
	v_mfma_f32_16x16x32_bf16 v[50:53], v[184:187], v[180:183], v[50:53]
	ds_read_b128 v[184:187], v205 offset:40960
	ds_read_b128 v[200:203], v205 offset:43008
	s_waitcnt lgkmcnt(4)
	v_mfma_f32_16x16x32_bf16 v[122:125], v[188:191], v[168:171], v[122:125]
	s_add_u32 m0, s9, 0x8000
	v_mfma_f32_16x16x32_bf16 v[106:109], v[188:191], v[172:175], v[106:109]
	global_load_lds_dwordx4 v166, s[10:11]
	v_add_u32_e32 v166, 0x80, v166
	v_mfma_f32_16x16x32_bf16 v[78:81], v[188:191], v[176:179], v[78:81]
	v_mfma_f32_16x16x32_bf16 v[42:45], v[188:191], v[180:183], v[42:45]
	s_waitcnt lgkmcnt(3)
	v_mfma_f32_16x16x32_bf16 v[118:121], v[192:195], v[168:171], v[118:121]
	s_add_u32 m0, s9, 0x2000
	v_mfma_f32_16x16x32_bf16 v[94:97], v[192:195], v[172:175], v[94:97]
	global_load_lds_dwordx4 v165, s[14:15]
	v_add_u32_e32 v165, 0x80, v165
	v_mfma_f32_16x16x32_bf16 v[58:61], v[192:195], v[176:179], v[58:61]
	v_mfma_f32_16x16x32_bf16 v[26:29], v[192:195], v[180:183], v[26:29]
	ds_read_b128 v[188:191], v205 offset:45056
	ds_read_b128 v[192:195], v205 offset:47104
	s_waitcnt lgkmcnt(4)
	v_mfma_f32_16x16x32_bf16 v[114:117], v[196:199], v[168:171], v[114:117]
	s_add_u32 m0, s9, 0xa000
	v_mfma_f32_16x16x32_bf16 v[90:93], v[196:199], v[172:175], v[90:93]
	global_load_lds_dwordx4 v164, s[10:11]
	v_add_u32_e32 v164, 0x80, v164
	v_mfma_f32_16x16x32_bf16 v[54:57], v[196:199], v[176:179], v[54:57]
	v_mfma_f32_16x16x32_bf16 v[22:25], v[196:199], v[180:183], v[22:25]
	v_add_u32_e32 v220, v204, v141
	s_waitcnt lgkmcnt(3)
	v_mfma_f32_16x16x32_bf16 v[102:105], v[184:187], v[168:171], v[102:105]
	ds_read_b128 v[196:199], v220 offset:32768
	ds_read_b128 v[204:207], v220 offset:34816
	s_add_u32 m0, s9, 0x4000
	v_mfma_f32_16x16x32_bf16 v[74:77], v[184:187], v[172:175], v[74:77]
	global_load_lds_dwordx4 v163, s[14:15]
	v_add_u32_e32 v163, 0x80, v163
	v_mfma_f32_16x16x32_bf16 v[46:49], v[184:187], v[176:179], v[46:49]
	v_mfma_f32_16x16x32_bf16 v[10:13], v[184:187], v[180:183], v[10:13]
	ds_read_b128 v[184:187], v136
	ds_read_b128 v[208:211], v136 offset:2048
	ds_read_b128 v[212:215], v136 offset:4096
	ds_read_b128 v[216:219], v136 offset:6144
	s_waitcnt lgkmcnt(8)
	v_mfma_f32_16x16x32_bf16 v[98:101], v[200:203], v[168:171], v[98:101]
	s_add_u32 m0, s9, 0xc000
	v_mfma_f32_16x16x32_bf16 v[66:69], v[200:203], v[172:175], v[66:69]
	global_load_lds_dwordx4 v162, s[10:11]
	v_add_u32_e32 v162, 0x80, v162
	v_mfma_f32_16x16x32_bf16 v[30:33], v[200:203], v[176:179], v[30:33]
	v_mfma_f32_16x16x32_bf16 v[6:9], v[200:203], v[180:183], v[6:9]
	s_waitcnt lgkmcnt(7)
	v_mfma_f32_16x16x32_bf16 v[70:73], v[188:191], v[168:171], v[70:73]
	s_add_u32 m0, s9, 0x6000
	s_waitcnt lgkmcnt(6)
	v_mfma_f32_16x16x32_bf16 v[62:65], v[192:195], v[168:171], v[62:65]
	global_load_lds_dwordx4 v161, s[14:15]
	v_add_u32_e32 v161, 0x80, v161
	v_mfma_f32_16x16x32_bf16 v[38:41], v[188:191], v[172:175], v[38:41]
	v_mfma_f32_16x16x32_bf16 v[34:37], v[192:195], v[172:175], v[34:37]
	ds_read_b128 v[168:171], v220 offset:36864
	ds_read_b128 v[172:175], v220 offset:38912
	v_mfma_f32_16x16x32_bf16 v[18:21], v[188:191], v[176:179], v[18:21]
	s_add_u32 m0, s9, 0xe000
	v_mfma_f32_16x16x32_bf16 v[14:17], v[192:195], v[176:179], v[14:17]
	global_load_lds_dwordx4 v160, s[10:11]
	v_add_u32_e32 v160, 0x80, v160
	v_mfma_f32_16x16x32_bf16 v[2:5], v[188:191], v[180:183], v[2:5]
	v_mfma_f32_16x16x32_bf16 v[86:89], v[192:195], v[180:183], v[86:89]
	ds_read_b128 v[176:179], v220 offset:40960
	ds_read_b128 v[180:183], v220 offset:43008
	s_waitcnt lgkmcnt(7)
	v_mfma_f32_16x16x32_bf16 v[126:129], v[196:199], v[184:187], v[126:129]
	v_mfma_f32_16x16x32_bf16 v[122:125], v[204:207], v[184:187], v[122:125]
	s_waitcnt lgkmcnt(6)
	v_mfma_f32_16x16x32_bf16 v[110:113], v[196:199], v[208:211], v[110:113]
	v_mfma_f32_16x16x32_bf16 v[106:109], v[204:207], v[208:211], v[106:109]
	s_waitcnt lgkmcnt(5)
	v_mfma_f32_16x16x32_bf16 v[82:85], v[196:199], v[212:215], v[82:85]
	v_mfma_f32_16x16x32_bf16 v[78:81], v[204:207], v[212:215], v[78:81]
	s_waitcnt lgkmcnt(4)
	v_mfma_f32_16x16x32_bf16 v[50:53], v[196:199], v[216:219], v[50:53]
	v_mfma_f32_16x16x32_bf16 v[42:45], v[204:207], v[216:219], v[42:45]
	s_waitcnt lgkmcnt(3)
	v_mfma_f32_16x16x32_bf16 v[118:121], v[168:171], v[184:187], v[118:121]
	v_mfma_f32_16x16x32_bf16 v[94:97], v[168:171], v[208:211], v[94:97]
	v_mfma_f32_16x16x32_bf16 v[58:61], v[168:171], v[212:215], v[58:61]
	v_mfma_f32_16x16x32_bf16 v[26:29], v[168:171], v[216:219], v[26:29]
	ds_read_b128 v[168:171], v220 offset:45056
	ds_read_b128 v[188:191], v220 offset:47104
	s_waitcnt lgkmcnt(4)
; template <bool SWAP, class Epi, bool THIN = false> ...
;     ...
;     for (int st = 0; st < ns; ++st) {
;       asm volatile("s_waitcnt vmcnt(0)" ::: "memory");
;       __builtin_amdgcn_s_barrier();
;       asm volatile("" ::: "memory");
;       if (st + 1 < ns) {
;         char* nb = smem + ((st + 1) & 1) * 65536;
;         const int ko = (st + 1) * 64;
; #pragma unroll
;         for (int i = 0; i < 4; ++i) { GLDS16(A + (size_t)(ap[i] + ko), nb + tid * 16 + i * 8192); GLDS16(Bt + (size_t)(bp[i] + ko), nb + 32768 + tid * 16 + i * 8192); }
;       }
;       const char* sa = smem + (st & 1) * 65536 + (wr * 64 + fr) * 128;
;       const char* sb = smem + (st & 1) * 65536 + 32768 + (wc * 128 + fr) * 128;
;       if constexpr (THIN) {
;         if (wc == 0) {
; #pragma unroll
;           for (int ks = 0; ks < 2; ++ks) {
;             bf16x8 af[4], bf[2];
; #pragma unroll
;             for (int m = 0; m < 4; ++m) af[m] = *(const bf16x8*)(sa + m * 2048 + (((ks * 4 + fq) ^ swz) << 4));
; #pragma unroll
;             for (int n = 0; n < 2; ++n) bf[n] = *(const bf16x8*)(sb + n * 2048 + (((ks * 4 + fq) ^ swz) << 4));
; #pragma unroll
;             for (int m = 0; m < 4; ++m)
; #pragma unroll
;               for (int n = 0; n < 2; ++n)
;                 acc[m][n] = SWAP ? __builtin_amdgcn_mfma_f32_16x16x32_bf16(bf[n], af[m], acc[m][n], 0, 0, 0)
;                                  : __builtin_amdgcn_mfma_f32_16x16x32_bf16(af[m], bf[n], acc[m][n], 0, 0, 0);
;           }
;         }
;       } else {
;       bf16x8 afA[4], afB[4], bfb[2][2];
; #pragma unroll
;       for (int m = 0; m < 4; ++m) afA[m] = *(const bf16x8*)(sa + m * 2048 + ((fq ^ swz) << 4));
; #pragma unroll
;       for (int n = 0; n < 2; ++n) bfb[0][n] = *(const bf16x8*)(sb + n * 2048 + ((fq ^ swz) << 4));
; #pragma unroll
;       for (int gq = 0; gq < 8; ++gq) {
;         const int ks = gq >> 2, nh = gq & 3;
;         if (gq < 7) {
;           const int ks2 = (gq + 1) >> 2, nh2 = (gq + 1) & 3;
; #pragma unroll
;           for (int n = 0; n < 2; ++n) bfb[(gq + 1) & 1][n] = *(const bf16x8*)(sb + (nh2 * 2 + n) * 2048 + (((ks2 * 4 + fq) ^ swz) << 4));
;         }
;         if (gq == 3) {
; #pragma unroll
;           for (int m = 0; m < 4; ++m) afB[m] = *(const bf16x8*)(sa + m * 2048 + (((4 + fq) ^ swz) << 4));
;         }
;         __builtin_amdgcn_sched_barrier(0);
; #pragma unroll
	v_mfma_f32_16x16x32_bf16 v[114:117], v[172:175], v[184:187], v[114:117]
	v_mfma_f32_16x16x32_bf16 v[90:93], v[172:175], v[208:211], v[90:93]
	v_mfma_f32_16x16x32_bf16 v[54:57], v[172:175], v[212:215], v[54:57]
	v_mfma_f32_16x16x32_bf16 v[22:25], v[172:175], v[216:219], v[22:25]
	s_waitcnt lgkmcnt(3)
	v_mfma_f32_16x16x32_bf16 v[102:105], v[176:179], v[184:187], v[102:105]
	s_waitcnt lgkmcnt(2)
	v_mfma_f32_16x16x32_bf16 v[98:101], v[180:183], v[184:187], v[98:101]
	v_mfma_f32_16x16x32_bf16 v[74:77], v[176:179], v[208:211], v[74:77]
	v_mfma_f32_16x16x32_bf16 v[66:69], v[180:183], v[208:211], v[66:69]
	v_mfma_f32_16x16x32_bf16 v[46:49], v[176:179], v[212:215], v[46:49]
	v_mfma_f32_16x16x32_bf16 v[30:33], v[180:183], v[212:215], v[30:33]
	v_mfma_f32_16x16x32_bf16 v[10:13], v[176:179], v[216:219], v[10:13]
	v_mfma_f32_16x16x32_bf16 v[6:9], v[180:183], v[216:219], v[6:9]
	s_waitcnt lgkmcnt(1)
	v_mfma_f32_16x16x32_bf16 v[70:73], v[168:171], v[184:187], v[70:73]
	s_add_i32 s5, s5, 64
	s_cmpk_eq_i32 s5, 0x3c0
	s_mov_b32 s7, s8
	s_waitcnt lgkmcnt(0)
	v_mfma_f32_16x16x32_bf16 v[62:65], v[188:191], v[184:187], v[62:65]
	v_mfma_f32_16x16x32_bf16 v[38:41], v[168:171], v[208:211], v[38:41]
	v_mfma_f32_16x16x32_bf16 v[34:37], v[188:191], v[208:211], v[34:37]
	v_mfma_f32_16x16x32_bf16 v[18:21], v[168:171], v[212:215], v[18:21]
	v_mfma_f32_16x16x32_bf16 v[14:17], v[188:191], v[212:215], v[14:17]
	v_mfma_f32_16x16x32_bf16 v[2:5], v[168:171], v[216:219], v[2:5]
	v_mfma_f32_16x16x32_bf16 v[86:89], v[188:191], v[216:219], v[86:89]
	s_cbranch_scc0 .LBB0_3424
	s_waitcnt vmcnt(0)
	s_barrier
	v_add_u32_e32 v136, v150, v140
	ds_read_b128 v[160:163], v136
	ds_read_b128 v[164:167], v136 offset:2048
	ds_read_b128 v[168:171], v136 offset:4096
	ds_read_b128 v[172:175], v136 offset:6144
	v_add_u32_e32 v136, v151, v140
	ds_read_b128 v[176:179], v136
	ds_read_b128 v[180:183], v136 offset:2048
	ds_read_b128 v[184:187], v136 offset:4096
	ds_read_b128 v[188:191], v136 offset:6144
	s_waitcnt lgkmcnt(0)
	v_mfma_f32_16x16x32_bf16 v[126:129], v[176:179], v[160:163], v[126:129]
	v_mfma_f32_16x16x32_bf16 v[110:113], v[176:179], v[164:167], v[110:113]
	v_mfma_f32_16x16x32_bf16 v[82:85], v[176:179], v[168:171], v[82:85]
	v_mfma_f32_16x16x32_bf16 v[50:53], v[176:179], v[172:175], v[50:53]
	ds_read_b128 v[176:179], v136 offset:8192
	ds_read_b128 v[192:195], v136 offset:10240
	v_mfma_f32_16x16x32_bf16 v[122:125], v[180:183], v[160:163], v[122:125]
	v_mfma_f32_16x16x32_bf16 v[106:109], v[180:183], v[164:167], v[106:109]
	v_mfma_f32_16x16x32_bf16 v[78:81], v[180:183], v[168:171], v[78:81]
	v_mfma_f32_16x16x32_bf16 v[42:45], v[180:183], v[172:175], v[42:45]
	v_mfma_f32_16x16x32_bf16 v[118:121], v[184:187], v[160:163], v[118:121]
	v_mfma_f32_16x16x32_bf16 v[94:97], v[184:187], v[164:167], v[94:97]
	v_mfma_f32_16x16x32_bf16 v[58:61], v[184:187], v[168:171], v[58:61]
	v_mfma_f32_16x16x32_bf16 v[26:29], v[184:187], v[172:175], v[26:29]
	ds_read_b128 v[180:183], v136 offset:12288
	ds_read_b128 v[184:187], v136 offset:14336
	v_mfma_f32_16x16x32_bf16 v[114:117], v[188:191], v[160:163], v[114:117]
	v_mfma_f32_16x16x32_bf16 v[90:93], v[188:191], v[164:167], v[90:93]
	v_mfma_f32_16x16x32_bf16 v[54:57], v[188:191], v[168:171], v[54:57]
	v_mfma_f32_16x16x32_bf16 v[22:25], v[188:191], v[172:175], v[22:25]
	v_add_u32_e32 v136, v151, v141
	v_add_u32_e32 v208, v150, v141
	s_waitcnt lgkmcnt(0)
	v_mfma_f32_16x16x32_bf16 v[102:105], v[176:179], v[160:163], v[102:105]
	v_mfma_f32_16x16x32_bf16 v[74:77], v[176:179], v[164:167], v[74:77]
	v_mfma_f32_16x16x32_bf16 v[188:191], v[192:195], v[164:167], v[66:69]
	v_mfma_f32_16x16x32_bf16 v[196:199], v[176:179], v[168:171], v[46:49]
	s_nop 2
	ds_read_b128 v[46:49], v136
	ds_read_b128 v[66:69], v136 offset:2048
	v_mfma_f32_16x16x32_bf16 v[10:13], v[176:179], v[172:175], v[10:13]
	ds_read_b128 v[176:179], v208
	ds_read_b128 v[200:203], v208 offset:2048
	ds_read_b128 v[204:207], v208 offset:4096
	ds_read_b128 v[208:211], v208 offset:6144
	v_mfma_f32_16x16x32_bf16 v[98:101], v[192:195], v[160:163], v[98:101]
	v_mfma_f32_16x16x32_bf16 v[30:33], v[192:195], v[168:171], v[30:33]
	v_mfma_f32_16x16x32_bf16 v[6:9], v[192:195], v[172:175], v[6:9]
	v_mfma_f32_16x16x32_bf16 v[192:195], v[180:183], v[164:167], v[38:41]
	v_mfma_f32_16x16x32_bf16 v[164:167], v[184:187], v[164:167], v[34:37]
	v_mfma_f32_16x16x32_bf16 v[18:21], v[180:183], v[168:171], v[18:21]
	v_mfma_f32_16x16x32_bf16 v[168:171], v[184:187], v[168:171], v[14:17]
	s_nop 2
	ds_read_b128 v[14:17], v136 offset:4096
	ds_read_b128 v[34:37], v136 offset:6144
	v_mfma_f32_16x16x32_bf16 v[70:73], v[180:183], v[160:163], v[70:73]
	v_mfma_f32_16x16x32_bf16 v[2:5], v[180:183], v[172:175], v[2:5]
	v_mfma_f32_16x16x32_bf16 v[160:163], v[184:187], v[160:163], v[62:65]
	v_mfma_f32_16x16x32_bf16 v[86:89], v[184:187], v[172:175], v[86:89]
	s_waitcnt lgkmcnt(0)
	v_mfma_f32_16x16x32_bf16 v[172:175], v[46:49], v[208:211], v[50:53]
	s_nop 2
	ds_read_b128 v[50:53], v136 offset:8192
	ds_read_b128 v[180:183], v136 offset:10240
	v_mfma_f32_16x16x32_bf16 v[126:129], v[46:49], v[176:179], v[126:129]
	v_mfma_f32_16x16x32_bf16 v[122:125], v[66:69], v[176:179], v[122:125]
	v_mfma_f32_16x16x32_bf16 v[110:113], v[46:49], v[200:203], v[110:113]
	v_mfma_f32_16x16x32_bf16 v[106:109], v[66:69], v[200:203], v[106:109]
	v_mfma_f32_16x16x32_bf16 v[82:85], v[46:49], v[204:207], v[82:85]
	v_mfma_f32_16x16x32_bf16 v[78:81], v[66:69], v[204:207], v[78:81]
	v_mfma_f32_16x16x32_bf16 v[184:187], v[66:69], v[208:211], v[42:45]
	ds_read_b128 v[224:227], v136 offset:12288
	ds_read_b128 v[228:231], v136 offset:14336
	v_mfma_f32_16x16x32_bf16 v[118:121], v[14:17], v[176:179], v[118:121]
	v_mfma_f32_16x16x32_bf16 v[114:117], v[34:37], v[176:179], v[114:117]
	v_mfma_f32_16x16x32_bf16 v[94:97], v[14:17], v[200:203], v[94:97]
	v_mfma_f32_16x16x32_bf16 v[90:93], v[34:37], v[200:203], v[90:93]
	v_mfma_f32_16x16x32_bf16 v[212:215], v[14:17], v[204:207], v[58:61]
	v_mfma_f32_16x16x32_bf16 v[216:219], v[34:37], v[204:207], v[54:57]
	v_mfma_f32_16x16x32_bf16 v[220:223], v[14:17], v[208:211], v[26:29]
	v_mfma_f32_16x16x32_bf16 v[66:69], v[34:37], v[208:211], v[22:25]
	s_waitcnt lgkmcnt(0)
	v_mfma_f32_16x16x32_bf16 v[38:41], v[180:183], v[204:207], v[30:33]
	v_mfma_f32_16x16x32_bf16 v[62:65], v[50:53], v[176:179], v[102:105]
	v_mfma_f32_16x16x32_bf16 v[46:49], v[180:183], v[176:179], v[98:101]
	v_mfma_f32_16x16x32_bf16 v[58:61], v[50:53], v[200:203], v[74:77]
	v_mfma_f32_16x16x32_bf16 v[42:45], v[180:183], v[200:203], v[188:191]
	v_mfma_f32_16x16x32_bf16 v[54:57], v[50:53], v[204:207], v[196:199]
	v_mfma_f32_16x16x32_bf16 v[50:53], v[50:53], v[208:211], v[10:13]
	v_mfma_f32_16x16x32_bf16 v[34:37], v[180:183], v[208:211], v[6:9]
	s_nop 2
	v_mov_b32_e32 v8, v1
	s_waitcnt vmcnt(0)
	s_barrier
; template <bool SWAP, class Epi, bool THIN = false> ...
;     ...
;     const int te = get_tid512();
;     const int fr_e = te & 15, fq_e = (te & 63) >> 4, wr_e = te >> 7, wc_e = (te >> 6) & 1;
;     const int sub = 2 * mt + (wr_e >> 1);
;     const int g = sub / tpg, ti = sub - g * tpg;
;     const int rig0 = ti * step - halo;
;     const int rw = (wr_e & 1) * 64;
;     if constexpr (Epi::KIND == 0) {
; #pragma unroll
;       for (int m = 0; m < 4; ++m) {
;         const int rig = rig0 + rw + m * 16 + fr_e;
;         if constexpr (Epi::ROWSUM) {
;           float ss = 0.f;
; #pragma unroll
;           for (int n = 0; n < 8; ++n) {
;             const int col = nt * 256 + wc_e * 128 + n * 16 + fq_e * 4;
;             if (col < N) ss += epi.c4(g, rig, col, acc[m][n]);
;           }
;           ss += __shfl_xor(ss, 16); ss += __shfl_xor(ss, 32);
;           if (fq_e == 0) epi.rowsum(g, rig, nt * 2 + wc_e, ss);
;         } else {
; #pragma unroll
;           for (int n = 0; n < 8; ++n) {
;             const int col = nt * 256 + wc_e * 128 + n * 16 + fq_e * 4;
;             if (col < N) epi.c4(g, rig, col, acc[m][n]);
;           }
;         }
;       }
;     } else if constexpr (Epi::KIND == 1) {
; #pragma unroll
;       for (int m = 0; m < 4; ++m) {
;         const int rig = rig0 + rw + m * 16 + fq_e * 4;
; #pragma unroll
;         for (int n = 0; n < 8; ++n) {
;           const int col = nt * 256 + wc_e * 128 + n * 16 + fr_e;
;           if (col < N) epi.r4(g, rig, col, acc[m][n]);
;         }
;       }
;     } else {
;       bf16_t* Zw = (bf16_t*)smem + ((wr_e >> 1) * 2 + wc_e) * (128 * 132);
;       const int nt2w = nt * 2 + wc_e;
; #pragma unroll
;       for (int n = 0; n < 8; ++n) {
;         const int cl = n * 16 + fq_e * 4;
;         f32x4 b4 = {0.f, 0.f, 0.f, 0.f};
;         if (epi.pre_bias) b4 = *(const f32x4*)(epi.pre_bias + epi.norig(nt2w, cl));
; #pragma unroll
;         for (int m = 0; m < 4; ++m) {
;           const int rl = rw + m * 16 + fr_e;
;           const int pos = rig0 + rl;
;           const bool ok = pos >= 0 && pos < grows;
;           f32x4 vv = acc[m][n] + b4;
;           if (!ok) vv = (f32x4){0.f, 0.f, 0.f, 0.f};
;           uint2 u; u.x = pack2(vv[0], vv[1]); u.y = pack2(vv[2], vv[3]);
;           *(uint2*)(Zw + rl * 132 + cl) = u;
;         }
	v_mfma_f32_16x16x32_bf16 v[30:33], v[224:227], v[176:179], v[70:73]
	v_ashrrev_i32_e32 v98, 8, v8
	v_add_u32_e32 v6, s4, v98
	v_mul_hi_i32 v7, v6, s26
	v_lshrrev_b32_e32 v9, 31, v7
	v_ashrrev_i32_e32 v7, 3, v7
	v_add_u32_e32 v70, v7, v9
	v_and_b32_e32 v71, 15, v8
	v_mad_u64_u32 v[6:7], s[4:5], v70, s27, v[6:7]
	v_lshrrev_b32_e32 v74, 1, v8
	v_bfe_u32 v73, v8, 6, 1
	v_mul_lo_u32 v72, v6, s28
	v_and_or_b32 v71, v74, 64, v71
	v_add_u32_e32 v99, v72, v71
	v_lshl_or_b32 v73, v98, 1, v73
	v_mul_lo_u32 v73, v73, s29
	v_add_u32_e32 v100, -1, v99
	v_and_or_b32 v73, v74, 24, v73
	v_pk_add_f32 v[74:75], v[128:129], 0 op_sel_hi:[1,0]
	v_pk_add_f32 v[76:77], v[126:127], 0 op_sel_hi:[1,0]
	v_cmp_gt_u32_e32 vcc, s30, v100
	v_mfma_f32_16x16x32_bf16 v[22:25], v[224:227], v[204:207], v[18:21]
	v_mad_u32_u24 v71, v71, s31, v73
	v_add_u32_e32 v73, 15, v99
	v_cmp_gt_u32_e64 s[4:5], s30, v73
	v_mfma_f32_16x16x32_bf16 v[18:21], v[224:227], v[208:211], v[2:5]
	s_lshl_b32 s24, s6, 7
	v_cndmask_b32_e32 v75, 0, v75, vcc
	v_pk_add_f32 v[84:85], v[84:85], 0 op_sel_hi:[1,0]
	v_mfma_f32_16x16x32_bf16 v[2:5], v[228:231], v[208:211], v[86:89]
	v_add_f32_e64 v82, v82, 0
	v_add_f32_e64 v83, v83, 0
	v_pk_add_f32 v[66:67], v[66:67], 0 op_sel_hi:[1,0]
	v_pk_add_f32 v[62:63], v[62:63], 0 op_sel_hi:[1,0]
	v_cndmask_b32_e32 v86, 0, v74, vcc
	v_cndmask_b32_e32 v74, 0, v76, vcc
	v_cndmask_b32_e32 v76, 0, v77, vcc
	v_cvt_pk_bf16_f32 v74, v74, v76
	v_pk_add_f32 v[76:77], v[112:113], 0 op_sel_hi:[1,0]
	v_cvt_pk_bf16_f32 v75, v86, v75
	v_pk_add_f32 v[86:87], v[110:111], 0 op_sel_hi:[1,0]
	v_cndmask_b32_e64 v73, 0, v76, s[4:5]
	v_cndmask_b32_e64 v77, 0, v77, s[4:5]
	v_cvt_pk_bf16_f32 v77, v73, v77
	v_add_u32_e32 v73, 31, v99
	v_cmp_gt_u32_e64 s[6:7], s30, v73
	v_cndmask_b32_e64 v76, 0, v86, s[4:5]
	v_cndmask_b32_e64 v86, 0, v87, s[4:5]
	v_cndmask_b32_e64 v73, 0, v84, s[6:7]
	v_cndmask_b32_e64 v82, 0, v82, s[6:7]
	v_cndmask_b32_e64 v83, 0, v83, s[6:7]
	v_cndmask_b32_e64 v84, 0, v85, s[6:7]
	v_cvt_pk_bf16_f32 v82, v82, v83
	v_cvt_pk_bf16_f32 v83, v73, v84
	v_add_u32_e32 v73, 47, v99
	v_cvt_pk_bf16_f32 v76, v76, v86
	v_pk_add_f32 v[84:85], v[174:175], 0 op_sel_hi:[1,0]
	v_pk_add_f32 v[86:87], v[172:173], 0 op_sel_hi:[1,0]
	v_cmp_gt_u32_e64 s[8:9], s30, v73
	v_pk_add_f32 v[88:89], v[122:123], 0 op_sel_hi:[1,0]
	v_mfma_f32_16x16x32_bf16 v[26:29], v[224:227], v[200:203], v[192:195]
	v_cndmask_b32_e64 v73, 0, v84, s[8:9]
	v_cndmask_b32_e64 v84, 0, v86, s[8:9]
	v_cndmask_b32_e64 v86, 0, v87, s[8:9]
	v_cndmask_b32_e64 v85, 0, v85, s[8:9]
	v_cvt_pk_bf16_f32 v84, v84, v86
	v_pk_add_f32 v[86:87], v[124:125], 0 op_sel_hi:[1,0]
	v_cvt_pk_bf16_f32 v85, v73, v85
	v_mfma_f32_16x16x32_bf16 v[14:17], v[228:231], v[176:179], v[160:163]
	v_cndmask_b32_e32 v73, 0, v86, vcc
	v_cndmask_b32_e32 v87, 0, v87, vcc
	v_cndmask_b32_e32 v86, 0, v88, vcc
	v_cndmask_b32_e32 v88, 0, v89, vcc
	v_cvt_pk_bf16_f32 v86, v86, v88
	v_cvt_pk_bf16_f32 v87, v73, v87
	ds_write2_b64 v71, v[74:75], v[86:87] offset1:4
	v_pk_add_f32 v[74:75], v[108:109], 0 op_sel_hi:[1,0]
	v_pk_add_f32 v[86:87], v[106:107], 0 op_sel_hi:[1,0]
	v_cndmask_b32_e64 v73, 0, v74, s[4:5]
	v_cndmask_b32_e64 v75, 0, v75, s[4:5]
	v_cndmask_b32_e64 v74, 0, v86, s[4:5]
	v_cndmask_b32_e64 v86, 0, v87, s[4:5]
	v_cvt_pk_bf16_f32 v74, v74, v86
	v_cvt_pk_bf16_f32 v75, v73, v75
	v_add_u32_e32 v73, 0x1000, v71
	ds_write2_b64 v73, v[76:77], v[74:75] offset0:16 offset1:20
	v_pk_add_f32 v[74:75], v[80:81], 0 op_sel_hi:[1,0]
	v_pk_add_f32 v[76:77], v[78:79], 0 op_sel_hi:[1,0]
	v_cndmask_b32_e64 v78, 0, v74, s[6:7]
	v_cndmask_b32_e64 v75, 0, v75, s[6:7]
	v_cndmask_b32_e64 v74, 0, v76, s[6:7]
	v_cndmask_b32_e64 v76, 0, v77, s[6:7]
	v_cvt_pk_bf16_f32 v74, v74, v76
	v_cvt_pk_bf16_f32 v75, v78, v75
	v_add_u32_e32 v86, 0x2000, v71
	ds_write2_b64 v86, v[82:83], v[74:75] offset0:32 offset1:36
	v_pk_add_f32 v[74:75], v[186:187], 0 op_sel_hi:[1,0]
	v_pk_add_f32 v[76:77], v[184:185], 0 op_sel_hi:[1,0]
	v_cndmask_b32_e64 v78, 0, v74, s[8:9]
	v_cndmask_b32_e64 v75, 0, v75, s[8:9]
	v_cndmask_b32_e64 v74, 0, v76, s[8:9]
	v_cndmask_b32_e64 v76, 0, v77, s[8:9]
	v_cvt_pk_bf16_f32 v74, v74, v76
	v_cvt_pk_bf16_f32 v75, v78, v75
	v_add_u32_e32 v87, 0x3000, v71
	ds_write2_b64 v87, v[84:85], v[74:75] offset0:48 offset1:52
	v_pk_add_f32 v[74:75], v[120:121], 0 op_sel_hi:[1,0]
	v_pk_add_f32 v[76:77], v[118:119], 0 op_sel_hi:[1,0]
	v_cndmask_b32_e32 v78, 0, v74, vcc
	v_cndmask_b32_e32 v75, 0, v75, vcc
	v_cndmask_b32_e32 v74, 0, v76, vcc
	v_cndmask_b32_e32 v76, 0, v77, vcc
	v_cvt_pk_bf16_f32 v74, v74, v76
	v_cvt_pk_bf16_f32 v75, v78, v75
	v_pk_add_f32 v[76:77], v[96:97], 0 op_sel_hi:[1,0]
	v_pk_add_f32 v[78:79], v[94:95], 0 op_sel_hi:[1,0]
	v_cndmask_b32_e64 v80, 0, v76, s[4:5]
	v_cndmask_b32_e64 v77, 0, v77, s[4:5]
	v_cndmask_b32_e64 v76, 0, v78, s[4:5]
	v_cndmask_b32_e64 v78, 0, v79, s[4:5]
	v_cvt_pk_bf16_f32 v76, v76, v78
	v_cvt_pk_bf16_f32 v77, v80, v77
	v_pk_add_f32 v[78:79], v[214:215], 0 op_sel_hi:[1,0]
	v_pk_add_f32 v[80:81], v[212:213], 0 op_sel_hi:[1,0]
	v_cndmask_b32_e64 v82, 0, v78, s[6:7]
	v_cndmask_b32_e64 v79, 0, v79, s[6:7]
	v_cndmask_b32_e64 v78, 0, v80, s[6:7]
	v_cndmask_b32_e64 v80, 0, v81, s[6:7]
	v_cvt_pk_bf16_f32 v78, v78, v80
	v_cvt_pk_bf16_f32 v79, v82, v79
	v_pk_add_f32 v[80:81], v[222:223], 0 op_sel_hi:[1,0]
	v_pk_add_f32 v[82:83], v[220:221], 0 op_sel_hi:[1,0]
	v_cndmask_b32_e64 v84, 0, v80, s[8:9]
	v_cndmask_b32_e64 v81, 0, v81, s[8:9]
	v_cndmask_b32_e64 v80, 0, v82, s[8:9]
	v_cndmask_b32_e64 v82, 0, v83, s[8:9]
	v_cvt_pk_bf16_f32 v80, v80, v82
	v_cvt_pk_bf16_f32 v81, v84, v81
	v_pk_add_f32 v[82:83], v[116:117], 0 op_sel_hi:[1,0]
	v_pk_add_f32 v[84:85], v[114:115], 0 op_sel_hi:[1,0]
; __device__ __forceinline__ unsigned pack2(float a, float b) { unsigned r; asm("v_cvt_pk_bf16_f32 %0, %1, %2" : "=v"(r) : "v"(a), "v"(b)); return r; }
; template <bool SWAP, class Epi, bool THIN = false> ...
;     ...
;       bf16_t* Zw = (bf16_t*)smem + ((wr_e >> 1) * 2 + wc_e) * (128 * 132);
;       const int nt2w = nt * 2 + wc_e;
; #pragma unroll
;       for (int n = 0; n < 8; ++n) {
;         const int cl = n * 16 + fq_e * 4;
;         f32x4 b4 = {0.f, 0.f, 0.f, 0.f};
;         if (epi.pre_bias) b4 = *(const f32x4*)(epi.pre_bias + epi.norig(nt2w, cl));
; #pragma unroll
;         for (int m = 0; m < 4; ++m) {
;           const int rl = rw + m * 16 + fr_e;
;           const int pos = rig0 + rl;
;           const bool ok = pos >= 0 && pos < grows;
;           f32x4 vv = acc[m][n] + b4;
;           if (!ok) vv = (f32x4){0.f, 0.f, 0.f, 0.f};
;           uint2 u; u.x = pack2(vv[0], vv[1]); u.y = pack2(vv[2], vv[3]);
;           *(uint2*)(Zw + rl * 132 + cl) = u;
;         }
	v_cndmask_b32_e32 v88, 0, v82, vcc
	v_cndmask_b32_e32 v83, 0, v83, vcc
	v_cndmask_b32_e32 v82, 0, v84, vcc
	v_mfma_f32_16x16x32_bf16 v[10:13], v[228:231], v[200:203], v[164:167]
	v_cndmask_b32_e32 v84, 0, v85, vcc
	v_cvt_pk_bf16_f32 v82, v82, v84
	v_cvt_pk_bf16_f32 v83, v88, v83
	v_mfma_f32_16x16x32_bf16 v[6:9], v[228:231], v[204:207], v[168:171]
	ds_write2_b64 v71, v[74:75], v[82:83] offset0:8 offset1:12
	v_pk_add_f32 v[74:75], v[92:93], 0 op_sel_hi:[1,0]
	v_pk_add_f32 v[82:83], v[90:91], 0 op_sel_hi:[1,0]
	v_cndmask_b32_e64 v84, 0, v74, s[4:5]
	v_cndmask_b32_e64 v75, 0, v75, s[4:5]
	v_cndmask_b32_e64 v74, 0, v82, s[4:5]
	v_cndmask_b32_e64 v82, 0, v83, s[4:5]
	v_cvt_pk_bf16_f32 v74, v74, v82
	v_cvt_pk_bf16_f32 v75, v84, v75
	v_pk_add_f32 v[28:29], v[28:29], 0 op_sel_hi:[1,0]
	v_pk_add_f32 v[26:27], v[26:27], 0 op_sel_hi:[1,0]
	ds_write2_b64 v73, v[76:77], v[74:75] offset0:24 offset1:28
	v_pk_add_f32 v[74:75], v[218:219], 0 op_sel_hi:[1,0]
	v_pk_add_f32 v[76:77], v[216:217], 0 op_sel_hi:[1,0]
	v_pk_add_f32 v[58:59], v[58:59], 0 op_sel_hi:[1,0]
	v_pk_add_f32 v[54:55], v[54:55], 0 op_sel_hi:[1,0]
	v_pk_add_f32 v[50:51], v[50:51], 0 op_sel_hi:[1,0]
	v_pk_add_f32 v[46:47], v[46:47], 0 op_sel_hi:[1,0]
	v_pk_add_f32 v[42:43], v[42:43], 0 op_sel_hi:[1,0]
	v_pk_add_f32 v[38:39], v[38:39], 0 op_sel_hi:[1,0]
	v_pk_add_f32 v[34:35], v[34:35], 0 op_sel_hi:[1,0]
	v_pk_add_f32 v[30:31], v[30:31], 0 op_sel_hi:[1,0]
	v_cndmask_b32_e64 v28, 0, v28, s[4:5]
	v_cndmask_b32_e64 v26, 0, v26, s[4:5]
	v_cndmask_b32_e64 v27, 0, v27, s[4:5]
	v_pk_add_f32 v[22:23], v[22:23], 0 op_sel_hi:[1,0]
	v_pk_add_f32 v[18:19], v[18:19], 0 op_sel_hi:[1,0]
	v_pk_add_f32 v[14:15], v[14:15], 0 op_sel_hi:[1,0]
	v_pk_add_f32 v[10:11], v[10:11], 0 op_sel_hi:[1,0]
	v_pk_add_f32 v[6:7], v[6:7], 0 op_sel_hi:[1,0]
	v_pk_add_f32 v[2:3], v[2:3], 0 op_sel_hi:[1,0]
	v_cndmask_b32_e64 v82, 0, v74, s[6:7]
	v_cndmask_b32_e64 v75, 0, v75, s[6:7]
	v_cndmask_b32_e64 v74, 0, v76, s[6:7]
	v_pk_add_f32 v[68:69], v[68:69], 0 op_sel_hi:[1,0]
	v_cndmask_b32_e64 v66, 0, v66, s[8:9]
	v_cndmask_b32_e64 v67, 0, v67, s[8:9]
	v_pk_add_f32 v[64:65], v[64:65], 0 op_sel_hi:[1,0]
	v_cndmask_b32_e32 v62, 0, v62, vcc
	v_cndmask_b32_e32 v63, 0, v63, vcc
	v_pk_add_f32 v[60:61], v[60:61], 0 op_sel_hi:[1,0]
	v_cndmask_b32_e64 v58, 0, v58, s[4:5]
	v_cndmask_b32_e64 v59, 0, v59, s[4:5]
	v_pk_add_f32 v[56:57], v[56:57], 0 op_sel_hi:[1,0]
	v_cndmask_b32_e64 v54, 0, v54, s[6:7]
	v_cndmask_b32_e64 v55, 0, v55, s[6:7]
	v_pk_add_f32 v[52:53], v[52:53], 0 op_sel_hi:[1,0]
	v_cndmask_b32_e64 v50, 0, v50, s[8:9]
	v_cndmask_b32_e64 v51, 0, v51, s[8:9]
	v_pk_add_f32 v[48:49], v[48:49], 0 op_sel_hi:[1,0]
	v_cndmask_b32_e32 v46, 0, v46, vcc
	v_cndmask_b32_e32 v47, 0, v47, vcc
	v_pk_add_f32 v[44:45], v[44:45], 0 op_sel_hi:[1,0]
	v_cndmask_b32_e64 v42, 0, v42, s[4:5]
	v_cndmask_b32_e64 v43, 0, v43, s[4:5]
	v_pk_add_f32 v[40:41], v[40:41], 0 op_sel_hi:[1,0]
	v_cndmask_b32_e64 v38, 0, v38, s[6:7]
	v_cndmask_b32_e64 v39, 0, v39, s[6:7]
	v_pk_add_f32 v[36:37], v[36:37], 0 op_sel_hi:[1,0]
	v_cndmask_b32_e64 v34, 0, v34, s[8:9]
	v_cndmask_b32_e64 v35, 0, v35, s[8:9]
	v_pk_add_f32 v[32:33], v[32:33], 0 op_sel_hi:[1,0]
	v_cndmask_b32_e32 v30, 0, v30, vcc
	v_cndmask_b32_e32 v31, 0, v31, vcc
	v_cndmask_b32_e64 v29, 0, v29, s[4:5]
	v_cvt_pk_bf16_f32 v26, v26, v27
	v_cvt_pk_bf16_f32 v27, v28, v29
	v_pk_add_f32 v[24:25], v[24:25], 0 op_sel_hi:[1,0]
	v_cndmask_b32_e64 v22, 0, v22, s[6:7]
	v_cndmask_b32_e64 v23, 0, v23, s[6:7]
	v_pk_add_f32 v[20:21], v[20:21], 0 op_sel_hi:[1,0]
	v_cndmask_b32_e64 v18, 0, v18, s[8:9]
	v_cndmask_b32_e64 v19, 0, v19, s[8:9]
	v_pk_add_f32 v[16:17], v[16:17], 0 op_sel_hi:[1,0]
	v_cndmask_b32_e32 v14, 0, v14, vcc
	v_cndmask_b32_e32 v15, 0, v15, vcc
	v_pk_add_f32 v[12:13], v[12:13], 0 op_sel_hi:[1,0]
	v_cndmask_b32_e64 v10, 0, v10, s[4:5]
	v_cndmask_b32_e64 v11, 0, v11, s[4:5]
	v_pk_add_f32 v[8:9], v[8:9], 0 op_sel_hi:[1,0]
	v_cndmask_b32_e64 v6, 0, v6, s[6:7]
	v_cndmask_b32_e64 v7, 0, v7, s[6:7]
	v_pk_add_f32 v[4:5], v[4:5], 0 op_sel_hi:[1,0]
	v_cndmask_b32_e64 v2, 0, v2, s[8:9]
	v_cndmask_b32_e64 v3, 0, v3, s[8:9]
	v_mov_b32_e32 v28, v142
	v_cndmask_b32_e64 v76, 0, v77, s[6:7]
	v_cvt_pk_bf16_f32 v74, v74, v76
	v_cvt_pk_bf16_f32 v75, v82, v75
	ds_write2_b64 v86, v[78:79], v[74:75] offset0:40 offset1:44
	v_cndmask_b32_e64 v68, 0, v68, s[8:9]
	v_cndmask_b32_e64 v69, 0, v69, s[8:9]
	v_cvt_pk_bf16_f32 v66, v66, v67
	v_cvt_pk_bf16_f32 v67, v68, v69
	ds_write2_b64 v87, v[80:81], v[66:67] offset0:56 offset1:60
	v_cndmask_b32_e32 v64, 0, v64, vcc
	v_cndmask_b32_e32 v65, 0, v65, vcc
	v_cvt_pk_bf16_f32 v62, v62, v63
	v_cvt_pk_bf16_f32 v63, v64, v65
	v_cndmask_b32_e64 v60, 0, v60, s[4:5]
	v_cndmask_b32_e64 v61, 0, v61, s[4:5]
	v_cvt_pk_bf16_f32 v58, v58, v59
	v_cvt_pk_bf16_f32 v59, v60, v61
	v_cndmask_b32_e64 v56, 0, v56, s[6:7]
	v_cndmask_b32_e64 v57, 0, v57, s[6:7]
	v_cvt_pk_bf16_f32 v54, v54, v55
	v_cvt_pk_bf16_f32 v55, v56, v57
	v_cndmask_b32_e64 v52, 0, v52, s[8:9]
	v_cndmask_b32_e64 v53, 0, v53, s[8:9]
	v_cvt_pk_bf16_f32 v50, v50, v51
	v_cvt_pk_bf16_f32 v51, v52, v53
	v_cndmask_b32_e32 v48, 0, v48, vcc
	v_cndmask_b32_e32 v49, 0, v49, vcc
	v_cvt_pk_bf16_f32 v46, v46, v47
	v_cvt_pk_bf16_f32 v47, v48, v49
	ds_write2_b64 v71, v[62:63], v[46:47] offset0:16 offset1:20
	v_cndmask_b32_e64 v44, 0, v44, s[4:5]
	v_cndmask_b32_e64 v45, 0, v45, s[4:5]
	v_cvt_pk_bf16_f32 v42, v42, v43
; __device__ __forceinline__ int get_tid() { int t = threadIdx.x & 255; asm volatile("" : "+v"(t)); return t; }
; __device__ __forceinline__ unsigned pack2(float a, float b) { unsigned r; asm("v_cvt_pk_bf16_f32 %0, %1, %2" : "=v"(r) : "v"(a), "v"(b)); return r; }
;   template <class F>
;   __device__ __forceinline__ void finish(const bf16_t* Z, int g, int rig0, int nt, F&& pre) const {
;     typedef f32x2_t f32x2;
;     const int tid = get_tid();
;     if (MODE == 0 || nt < 8) {
;       if (MODE == 0) {
;         const int f2 = (tid & 31) * 2, q8 = tid >> 5;
;         const int q0 = 1 + 16 * q8, q1 = (q0 + 16 < 127) ? q0 + 16 : 127;
;         const int na = norig(nt, f2), ng = norig(nt, 64 + f2);
;         const f32x2 a0 = *(const f32x2*)(cw + na), a1 = *(const f32x2*)(cw + NC + na), a2 = *(const f32x2*)(cw + 2 * NC + na), ab = *(const f32x2*)(cb + na);
;         const f32x2 g0 = *(const f32x2*)(cw + ng), g1 = *(const f32x2*)(cw + NC + ng), g2 = *(const f32x2*)(cw + 2 * NC + ng), gb = *(const f32x2*)(cb + ng);
;         pre();
;         f32x2 am = ldz(Z, q0 - 1, f2), ac = ldz(Z, q0, f2);
;         f32x2 gm = ldz(Z, q0 - 1, 64 + f2), gc = ldz(Z, q0, 64 + f2);
; template <bool SWAP, class Epi, bool THIN = false> ...
;     ...
;         for (int m = 0; m < 4; ++m) {
;           const int rl = rw + m * 16 + fr_e;
;           const int pos = rig0 + rl;
;           const bool ok = pos >= 0 && pos < grows;
;           f32x4 vv = acc[m][n] + b4;
;           if (!ok) vv = (f32x4){0.f, 0.f, 0.f, 0.f};
;           uint2 u; u.x = pack2(vv[0], vv[1]); u.y = pack2(vv[2], vv[3]);
;           *(uint2*)(Zw + rl * 132 + cl) = u;
;         }
;       }
;       __syncthreads();
	v_cvt_pk_bf16_f32 v43, v44, v45
	ds_write2_b64 v73, v[58:59], v[42:43] offset0:32 offset1:36
	v_cndmask_b32_e64 v40, 0, v40, s[6:7]
	v_cndmask_b32_e64 v41, 0, v41, s[6:7]
	v_cvt_pk_bf16_f32 v38, v38, v39
	v_cvt_pk_bf16_f32 v39, v40, v41
	ds_write2_b64 v86, v[54:55], v[38:39] offset0:48 offset1:52
	v_cndmask_b32_e64 v36, 0, v36, s[8:9]
	v_cndmask_b32_e64 v37, 0, v37, s[8:9]
	v_cvt_pk_bf16_f32 v34, v34, v35
	v_cvt_pk_bf16_f32 v35, v36, v37
	ds_write2_b64 v87, v[50:51], v[34:35] offset0:64 offset1:68
	v_cndmask_b32_e32 v32, 0, v32, vcc
	v_cndmask_b32_e32 v33, 0, v33, vcc
	v_cvt_pk_bf16_f32 v30, v30, v31
	v_cvt_pk_bf16_f32 v31, v32, v33
	v_cndmask_b32_e64 v24, 0, v24, s[6:7]
	v_cndmask_b32_e64 v25, 0, v25, s[6:7]
	v_cvt_pk_bf16_f32 v22, v22, v23
	v_cvt_pk_bf16_f32 v23, v24, v25
	v_cndmask_b32_e64 v20, 0, v20, s[8:9]
	v_cndmask_b32_e64 v21, 0, v21, s[8:9]
	v_cvt_pk_bf16_f32 v18, v18, v19
	v_cvt_pk_bf16_f32 v19, v20, v21
	v_cndmask_b32_e32 v16, 0, v16, vcc
	v_cndmask_b32_e32 v17, 0, v17, vcc
	v_cvt_pk_bf16_f32 v14, v14, v15
	v_cvt_pk_bf16_f32 v15, v16, v17
	ds_write2_b64 v71, v[30:31], v[14:15] offset0:24 offset1:28
	v_cndmask_b32_e64 v12, 0, v12, s[4:5]
	v_cndmask_b32_e64 v13, 0, v13, s[4:5]
	v_cvt_pk_bf16_f32 v10, v10, v11
	v_cvt_pk_bf16_f32 v11, v12, v13
	ds_write2_b64 v73, v[26:27], v[10:11] offset0:40 offset1:44
	v_cndmask_b32_e64 v8, 0, v8, s[6:7]
	v_cndmask_b32_e64 v9, 0, v9, s[6:7]
	v_cvt_pk_bf16_f32 v6, v6, v7
	v_cvt_pk_bf16_f32 v7, v8, v9
	ds_write2_b64 v86, v[22:23], v[6:7] offset0:56 offset1:60
	v_cndmask_b32_e64 v4, 0, v4, s[8:9]
	v_cndmask_b32_e64 v5, 0, v5, s[8:9]
	v_cvt_pk_bf16_f32 v2, v2, v3
	v_cvt_pk_bf16_f32 v3, v4, v5
	ds_write2_b64 v87, v[18:19], v[2:3] offset0:72 offset1:76
	s_waitcnt lgkmcnt(0)
	s_barrier
	v_mul_i32_i24_e32 v2, 0x10800, v98
	v_ashrrev_i32_e32 v29, 1, v28
	v_and_b32_e32 v38, -16, v29
	v_min_i32_e32 v3, 0x6e, v38
	v_or_b32_e32 v20, 1, v38
	v_add_u32_e32 v3, 17, v3
	v_cmp_lt_i32_e32 vcc, v20, v3
	v_ashrrev_i32_e32 v71, 31, v70
	s_and_saveexec_b64 s[4:5], vcc
	s_cbranch_execz .LBB0_3432
	v_lshlrev_b32_e32 v4, 1, v28
	v_and_b32_e32 v21, 62, v4
	v_or_b32_e32 v4, s24, v21
	s_add_i32 s6, s24, 0xb00
	v_ashrrev_i32_e32 v5, 31, v4
	v_or_b32_e32 v12, s6, v21
	v_lshlrev_b64 v[10:11], 2, v[4:5]
	v_lshl_add_u64 v[14:15], s[16:17], 0, v[10:11]
	v_lshl_add_u64 v[18:19], s[22:23], 0, v[10:11]
	v_ashrrev_i32_e32 v13, 31, v12
	v_lshl_add_u64 v[16:17], s[20:21], 0, v[10:11]
	global_load_dwordx2 v[4:5], v[14:15], off
	global_load_dwordx2 v[6:7], v[16:17], off
	global_load_dwordx2 v[8:9], v[18:19], off
	v_lshlrev_b64 v[18:19], 2, v[12:13]
	v_lshl_add_u64 v[10:11], s[18:19], 0, v[10:11]
	v_lshl_add_u64 v[22:23], s[16:17], 0, v[18:19]
	global_load_dwordx2 v[10:11], v[10:11], off
	v_lshl_add_u64 v[24:25], s[20:21], 0, v[18:19]
	v_lshl_add_u64 v[26:27], s[22:23], 0, v[18:19]
	global_load_dwordx2 v[12:13], v[22:23], off
	global_load_dwordx2 v[14:15], v[24:25], off
	global_load_dwordx2 v[16:17], v[26:27], off
	v_lshl_add_u64 v[18:19], s[18:19], 0, v[18:19]
	global_load_dwordx2 v[18:19], v[18:19], off
	v_mov_b32_e32 v117, 0
	v_lshlrev_b32_e32 v88, 1, v142
	v_and_b32_e32 v105, 62, v88
	v_add3_u32 v88, v105, s24, 64
	s_add_i32 s38, s24, 0xb40
	v_ashrrev_i32_e32 v89, 31, v88
	v_or_b32_e32 v96, s38, v105
	v_lshlrev_b64 v[94:95], 2, v[88:89]
	v_lshl_add_u64 v[98:99], s[16:17], 0, v[94:95]
	v_lshl_add_u64 v[102:103], s[22:23], 0, v[94:95]
	v_ashrrev_i32_e32 v97, 31, v96
	v_lshl_add_u64 v[100:101], s[20:21], 0, v[94:95]
	global_load_dwordx2 v[88:89], v[98:99], off
	global_load_dwordx2 v[90:91], v[100:101], off
	global_load_dwordx2 v[92:93], v[102:103], off
	v_lshlrev_b64 v[102:103], 2, v[96:97]
	v_lshl_add_u64 v[94:95], s[18:19], 0, v[94:95]
	v_lshl_add_u64 v[106:107], s[16:17], 0, v[102:103]
	global_load_dwordx2 v[94:95], v[94:95], off
	v_lshl_add_u64 v[108:109], s[20:21], 0, v[102:103]
	v_lshl_add_u64 v[110:111], s[22:23], 0, v[102:103]
	global_load_dwordx2 v[96:97], v[106:107], off
	global_load_dwordx2 v[98:99], v[108:109], off
	global_load_dwordx2 v[100:101], v[110:111], off
	v_lshl_add_u64 v[102:103], s[18:19], 0, v[102:103]
	global_load_dwordx2 v[102:103], v[102:103], off
	v_lshlrev_b32_e32 v136, 1, v21
	v_mul_lo_u32 v22, v38, s31
	v_mul_lo_u32 v20, v20, s31
	v_add3_u32 v22, v2, v22, v136
	v_add3_u32 v20, v2, v20, v136
	ds_read2_b32 v[22:23], v22 offset1:32
	ds_read2_b32 v[20:21], v20 offset1:32
	s_ashr_i32 s25, s24, 31
	s_lshl_b64 s[6:7], s[24:25], 1
	s_add_u32 s6, s12, s6
	s_addc_u32 s7, s13, s7
	v_lshrrev_b32_e32 v29, 4, v29
	v_and_b32_e32 v28, 31, v28
	s_waitcnt lgkmcnt(1)
	v_lshlrev_b32_e32 v32, 16, v23
	v_and_b32_e32 v33, 0xffff0000, v23
	v_lshlrev_b32_e32 v34, 16, v22
	v_and_b32_e32 v35, 0xffff0000, v22
	v_lshl_add_u64 v[22:23], s[6:7], 0, v[136:137]
	v_mad_u64_u32 v[30:31], s[6:7], v29, s33, v[2:3]
	v_lshlrev_b32_e32 v28, 2, v28
	s_waitcnt lgkmcnt(0)
	v_lshlrev_b32_e32 v24, 16, v21
	v_and_b32_e32 v25, 0xffff0000, v21
	v_lshlrev_b32_e32 v26, 16, v20
	v_and_b32_e32 v27, 0xffff0000, v20
	v_lshlrev_b64 v[20:21], 11, v[70:71]
	v_add3_u32 v39, v30, v28, s34
	s_mov_b32 s98, 0x1600
	s_mov_b32 s99, 0
	v_add_u32_e32 v48, v72, v38
	v_ashrrev_i32_e32 v49, 31, v48
	v_lshl_add_u64 v[48:49], v[20:21], 0, v[48:49]
	v_mad_u64_u32 v[50:51], s[38:39], v48, s35, v[22:23]
	v_mad_i32_i24 v51, v49, s35, v51
	s_mov_b64 s[6:7], 0
	s_waitcnt vmcnt(0)
	ds_read2_b32 v[44:45], v39 offset1:32
	s_branch .LBB0_3428

; __device__ __forceinline__ int get_tid() { int t = threadIdx.x & 255; asm volatile("" : "+v"(t)); return t; }
;   template <class F>
;   __device__ __forceinline__ void finish(const bf16_t* Z, int g, int rig0, int nt, F&& pre) const {
;     typedef f32x2_t f32x2;
;     const int tid = get_tid();
;     if (MODE == 0 || nt < 8) {
;       if (MODE == 0) {
;         const int f2 = (tid & 31) * 2, q8 = tid >> 5;
;         const int q0 = 1 + 16 * q8, q1 = (q0 + 16 < 127) ? q0 + 16 : 127;
;         const int na = norig(nt, f2), ng = norig(nt, 64 + f2);
;         const f32x2 a0 = *(const f32x2*)(cw + na), a1 = *(const f32x2*)(cw + NC + na), a2 = *(const f32x2*)(cw + 2 * NC + na), ab = *(const f32x2*)(cb + na);
;         const f32x2 g0 = *(const f32x2*)(cw + ng), g1 = *(const f32x2*)(cw + NC + ng), g2 = *(const f32x2*)(cw + 2 * NC + ng), gb = *(const f32x2*)(cb + ng);
;         pre();
;         f32x2 am = ldz(Z, q0 - 1, f2), ac = ldz(Z, q0, f2);
;         f32x2 gm = ldz(Z, q0 - 1, 64 + f2), gc = ldz(Z, q0, 64 + f2);
.LBB0_3432:
	s_waitcnt lgkmcnt(0)
	s_or_b64 exec, exec, s[4:5]
	v_mov_b32_e32 v3, v142
	s_nop 0
	v_ashrrev_i32_e32 v28, 1, v3
	v_and_b32_e32 v37, -16, v28
	v_min_i32_e32 v4, 0x6e, v37
	v_or_b32_e32 v20, 1, v37
	v_add_u32_e32 v36, 17, v4
	v_cmp_lt_i32_e32 vcc, v20, v36
	s_and_saveexec_b64 s[4:5], vcc
	s_cbranch_execz .LBB0_3418
	v_lshlrev_b32_e32 v4, 1, v3
	v_and_b32_e32 v21, 62, v4
	v_add3_u32 v4, v21, s24, 64
	s_add_i32 s6, s24, 0xb40
	v_ashrrev_i32_e32 v5, 31, v4
	v_or_b32_e32 v12, s6, v21
	v_lshlrev_b64 v[10:11], 2, v[4:5]
	v_lshl_add_u64 v[14:15], s[16:17], 0, v[10:11]
	v_lshl_add_u64 v[18:19], s[22:23], 0, v[10:11]
	v_ashrrev_i32_e32 v13, 31, v12
	v_lshl_add_u64 v[16:17], s[20:21], 0, v[10:11]
	v_lshlrev_b64 v[18:19], 2, v[12:13]
	v_lshl_add_u64 v[10:11], s[18:19], 0, v[10:11]
	v_lshl_add_u64 v[22:23], s[16:17], 0, v[18:19]
	v_lshl_add_u64 v[24:25], s[20:21], 0, v[18:19]
	v_lshl_add_u64 v[26:27], s[22:23], 0, v[18:19]
	v_lshl_add_u64 v[18:19], s[18:19], 0, v[18:19]
	v_lshlrev_b32_e32 v136, 1, v21
	v_mul_lo_u32 v22, v37, s31
	v_add3_u32 v22, v2, v22, v136
	v_mul_lo_u32 v20, v20, s31
	v_add_u32_e32 v22, 0x8400, v22
	v_add3_u32 v20, v2, v20, v136
	ds_read2_b32 v[22:23], v22 offset1:32
	v_add_u32_e32 v20, 0x8400, v20
	s_ashr_i32 s25, s24, 31
	ds_read2_b32 v[20:21], v20 offset1:32
	s_lshl_b64 s[6:7], s[24:25], 1
	s_add_u32 s6, s12, s6
	s_addc_u32 s7, s13, s7
	v_lshrrev_b32_e32 v28, 4, v28
	s_waitcnt lgkmcnt(1)
	v_lshlrev_b32_e32 v30, 16, v23
	v_and_b32_e32 v31, 0xffff0000, v23
	v_lshlrev_b32_e32 v32, 16, v22
	v_and_b32_e32 v33, 0xffff0000, v22
	v_lshl_add_u64 v[22:23], s[6:7], 0, v[136:137]
	v_mad_u64_u32 v[28:29], s[6:7], v28, s33, v[2:3]
	v_and_b32_e32 v2, 31, v3
	v_lshlrev_b32_e32 v2, 2, v2
	s_waitcnt lgkmcnt(0)
	v_lshlrev_b32_e32 v24, 16, v21
	v_and_b32_e32 v25, 0xffff0000, v21
	v_lshlrev_b32_e32 v26, 16, v20
	v_and_b32_e32 v27, 0xffff0000, v20
	v_lshlrev_b64 v[20:21], 11, v[70:71]
	v_add3_u32 v38, v28, v2, s36
	s_mov_b32 s98, 0x1600
	s_mov_b32 s99, 0
	v_add_u32_e32 v48, v72, v37
	v_ashrrev_i32_e32 v49, 31, v48
	v_lshl_add_u64 v[48:49], v[20:21], 0, v[48:49]
	v_mad_u64_u32 v[50:51], s[24:25], v48, s35, v[22:23]
	v_mad_i32_i24 v51, v49, s35, v51
	s_mov_b64 s[6:7], 0
	ds_read2_b32 v[44:45], v38 offset1:32
	s_branch .LBB0_3435

; __global__ void __launch_bounds__(512, 2) mega(P p_arg) {
;   __shared__ __attribute__((aligned(16))) char smem[LDS_BYTES];
	.amdhsa_kernel _Z4mega1P
		.amdhsa_group_segment_fixed_size 163840
		.amdhsa_private_segment_fixed_size 0
		.amdhsa_kernarg_size 816
		.amdhsa_user_sgpr_count 2
		.amdhsa_user_sgpr_dispatch_ptr 0
		.amdhsa_user_sgpr_queue_ptr 0
		.amdhsa_user_sgpr_kernarg_segment_ptr 1
		.amdhsa_user_sgpr_dispatch_id 0
		.amdhsa_user_sgpr_kernarg_preload_length 0
		.amdhsa_user_sgpr_kernarg_preload_offset 0
		.amdhsa_user_sgpr_private_segment_size 0
		.amdhsa_uses_dynamic_stack 0
		.amdhsa_enable_private_segment 0
		.amdhsa_system_sgpr_workgroup_id_x 1
		.amdhsa_system_sgpr_workgroup_id_y 0
		.amdhsa_system_sgpr_workgroup_id_z 0
		.amdhsa_system_sgpr_workgroup_info 0
		.amdhsa_system_vgpr_workitem_id 2
		.amdhsa_next_free_vgpr 256
		.amdhsa_next_free_sgpr 100
		.amdhsa_accum_offset 256
		.amdhsa_reserve_vcc 1
		.amdhsa_float_round_mode_32 0
		.amdhsa_float_round_mode_16_64 0
		.amdhsa_float_denorm_mode_32 3
		.amdhsa_float_denorm_mode_16_64 3
		.amdhsa_dx10_clamp 1
		.amdhsa_ieee_mode 1
		.amdhsa_fp16_overflow 0
		.amdhsa_tg_split 0
		.amdhsa_exception_fp_ieee_invalid_op 0
		.amdhsa_exception_fp_denorm_src 0
		.amdhsa_exception_fp_ieee_div_zero 0
		.amdhsa_exception_fp_ieee_overflow 0
		.amdhsa_exception_fp_ieee_underflow 0
		.amdhsa_exception_fp_ieee_inexact 0
		.amdhsa_exception_int_div_zero 0
	.end_amdhsa_kernel
